# clean_k6 + unit order as bit shuffle + LDS fragment-address adds hoisted out of the SwiGLU K-loops
# speedup vs baseline: 1.0051x; 1.0051x over previous
; #define PG8_STAGE(bufoff, gbase, voff) do { _Pragma("unroll") for (int _i = 0; _i < 2; ++_i) \
;         __builtin_amdgcn_global_load_lds((const unsigned*)((const char*)(gbase) + (voff)[_i]), (PG8_LAS unsigned*)(lds + (bufoff) + ldsw + _i * 8192), 16, 0, 0); } while (0)
; #define PG8_LDA(dst, b, h) do { _Pragma("unroll") for (int m = 0; m < 4; ++m) _Pragma("unroll") for (int k = 0; k < 2; ++k) dst[m][k] = *(const PG8_LAS bf16x8*)(lds + PG8_SA(b, h) + aoff + m * 2048 + k * 1024); } while (0)
; #define PG8_LDB(dst, b, h) do { _Pragma("unroll") for (int n = 0; n < 2; ++n) _Pragma("unroll") for (int k = 0; k < 2; ++k) dst[n][k] = *(const PG8_LAS bf16x8*)(lds + PG8_SB(b, h) + boff + n * 2048 + k * 1024); } while (0)
; #define PG8_WAIT_V(n) asm volatile("s_waitcnt vmcnt(" #n ")" ::: "memory")
; #define PG8_WAIT_L(n) asm volatile("s_waitcnt lgkmcnt(" #n ")" ::: "memory")
; #define PG8_BAR __builtin_amdgcn_s_barrier()
; #define PG8_SCHED __builtin_amdgcn_sched_barrier(0)
; template <class Epi, class Sched, bool ALIGN_EPI = false, bool SP2 = false>
; __device__ __forceinline__ void gemm_phase(PG8_LAS unsigned char* lds, const Gemm g, const Sched& S, const Epi& E) {
;     ...
;         const char* nA = has_next ? (const char*)g.A + (size_t)nxt.pm * tstep : cA; const char* nB = has_next ? (const char*)g.Bt + (size_t)nxt.pn * tstep : cB;
;         for (int t = 0; t < nt; t += 2) {
;             const bool last = (t == nt - 2);
;             const char* a1 = cA + (size_t)(t + 1) * kstep;
;             const char* a2 = last ? nA : cA + (size_t)(t + 2) * kstep; const char* b2 = last ? nB : cB + (size_t)(t + 2) * kstep;
;             const char* a3 = a2 + kstep; const char* b3 = b2 + kstep;
;             if (last && has_next) S.a_ready(nxt);
;             if constexpr (Epi::MID) { if (t == nt / 2) E.mid(acc, cur, wr, wc, fr, fq); }
;             if constexpr (SP2) {
;             PG8_LDB(B0, 0, 0); PG8_LDB(B1, 0, 1); PG8_SCHED; PG8_LDA(At, 0, 0); PG8_STAGE(PG8_SA(1, 1), a1 + hstep, voffA);
;             PG8_WAIT_V(8); PG8_WAIT_L(0); PG8_BAR; PG8_MMA(0, 0, At, B0); PG8_MMA(0, 1, At, B1); PG8_BAR; PG8_SCHED;
;             PG8_LDA(At, 0, 1); PG8_STAGE(PG8_SB(0, 0), b2, voffB); PG8_STAGE(PG8_SB(0, 1), b2 + hstep, voffB); PG8_STAGE(PG8_SA(0, 0), a2, voffA);
;             PG8_WAIT_V(8); PG8_WAIT_L(0); PG8_BAR; PG8_MMA(1, 0, At, B0); PG8_MMA(1, 1, At, B1); PG8_BAR; PG8_SCHED;
.LBB0_372:
	s_ashr_i32 s21, s20, 31
	s_lshl_b64 s[22:23], s[20:21], 20
	s_add_u32 s22, s8, s22
	s_addc_u32 s23, s9, s23
	s_and_b64 s[24:25], s[2:3], exec
	s_cselect_b32 s5, s23, s29
	s_cselect_b32 s11, s22, s28
	s_ashr_i32 s19, s18, 31
	s_lshl_b64 s[24:25], s[18:19], 20
	s_add_u32 s24, s35, s24
	s_addc_u32 s25, s36, s25
	s_and_b64 s[30:31], s[2:3], exec
	s_cselect_b32 s19, s25, s27
	s_cselect_b32 s21, s24, s26
	s_add_u32 s53, s26, 0x100
	s_addc_u32 s54, s27, 0
	s_add_u32 s26, s28, 0x80080
	s_addc_u32 s27, s29, 0
	s_mov_b32 s55, -2
	v_add_u32_e32 v226, 0x10000, v155
	s_add_u32 s28, s26, 0xfff80080
	s_addc_u32 s29, s27, -1
	s_add_i32 s33, 0, 0x10000
	s_cmp_eq_u32 s55, 28
	s_cselect_b32 s31, s5, s29
	s_cselect_b32 s30, s11, s28
	s_cselect_b32 s29, s19, s54
	s_cselect_b32 s28, s21, s53
	s_add_i32 s58, 0, 0x14000
	ds_read_b128 v[142:145], v226
	ds_read_b128 v[146:149], v226 offset:1024
	ds_read_b128 v[150:153], v226 offset:2048
	ds_read_b128 v[162:165], v226 offset:3072
	ds_read_b128 v[166:169], v226 offset:16384
	ds_read_b128 v[170:173], v226 offset:17408
	ds_read_b128 v[174:177], v226 offset:18432
	ds_read_b128 v[178:181], v226 offset:19456
	s_add_i32 m0, s41, 0xc000
	ds_read_b128 v[182:185], v160
	ds_read_b128 v[186:189], v160 offset:1024
	ds_read_b128 v[190:193], v160 offset:2048
	ds_read_b128 v[194:197], v160 offset:3072
	ds_read_b128 v[198:201], v160 offset:4096
	ds_read_b128 v[206:209], v160 offset:5120
	ds_read_b128 v[210:213], v160 offset:6144
	ds_read_b128 v[214:217], v160 offset:7168
	global_load_lds_dwordx4 v140, s[26:27]
	s_add_i32 m0, s41, 0xe000
	s_nop 0
	global_load_lds_dwordx4 v138, s[26:27]
	s_waitcnt vmcnt(8)
	s_waitcnt lgkmcnt(0)
	s_barrier
	s_setprio 1
	s_waitcnt lgkmcnt(0)
	v_mfma_f32_16x16x32_bf16 v[130:133], v[142:145], v[182:185], 0
	v_mfma_f32_16x16x32_bf16 v[130:133], v[146:149], v[186:189], v[130:133]
	v_mfma_f32_16x16x32_bf16 v[126:129], v[162:165], v[186:189], 0
	v_mfma_f32_16x16x32_bf16 v[126:129], v[150:153], v[182:185], v[126:129]
	v_mfma_f32_16x16x32_bf16 v[110:113], v[150:153], v[190:193], 0
	v_mfma_f32_16x16x32_bf16 v[110:113], v[162:165], v[194:197], v[110:113]
	v_mfma_f32_16x16x32_bf16 v[114:117], v[146:149], v[194:197], 0
	v_mfma_f32_16x16x32_bf16 v[114:117], v[142:145], v[190:193], v[114:117]
	v_mfma_f32_16x16x32_bf16 v[98:101], v[142:145], v[198:201], 0
	v_mfma_f32_16x16x32_bf16 v[98:101], v[146:149], v[206:209], v[98:101]
	v_mfma_f32_16x16x32_bf16 v[94:97], v[162:165], v[206:209], 0
	v_mfma_f32_16x16x32_bf16 v[94:97], v[150:153], v[198:201], v[94:97]
	v_mfma_f32_16x16x32_bf16 v[78:81], v[150:153], v[210:213], 0
	v_mfma_f32_16x16x32_bf16 v[78:81], v[162:165], v[214:217], v[78:81]
	v_mfma_f32_16x16x32_bf16 v[82:85], v[146:149], v[214:217], 0
	v_mfma_f32_16x16x32_bf16 v[82:85], v[142:145], v[210:213], v[82:85]
	s_setprio 0
	s_setprio 1
	v_mfma_f32_16x16x32_bf16 v[122:125], v[166:169], v[182:185], 0
	v_mfma_f32_16x16x32_bf16 v[122:125], v[170:173], v[186:189], v[122:125]
	v_mfma_f32_16x16x32_bf16 v[118:121], v[178:181], v[186:189], 0
	v_mfma_f32_16x16x32_bf16 v[118:121], v[174:177], v[182:185], v[118:121]
	v_mfma_f32_16x16x32_bf16 v[102:105], v[174:177], v[190:193], 0
	v_mfma_f32_16x16x32_bf16 v[102:105], v[178:181], v[194:197], v[102:105]
	v_mfma_f32_16x16x32_bf16 v[106:109], v[170:173], v[194:197], 0
	v_mfma_f32_16x16x32_bf16 v[106:109], v[166:169], v[190:193], v[106:109]
	v_mfma_f32_16x16x32_bf16 v[90:93], v[166:169], v[198:201], 0
	v_mfma_f32_16x16x32_bf16 v[90:93], v[170:173], v[206:209], v[90:93]
	v_mfma_f32_16x16x32_bf16 v[86:89], v[178:181], v[206:209], 0
	v_mfma_f32_16x16x32_bf16 v[86:89], v[174:177], v[198:201], v[86:89]
	v_mfma_f32_16x16x32_bf16 v[70:73], v[174:177], v[210:213], 0
	v_mfma_f32_16x16x32_bf16 v[70:73], v[178:181], v[214:217], v[70:73]
	v_mfma_f32_16x16x32_bf16 v[74:77], v[170:173], v[214:217], 0
	v_mfma_f32_16x16x32_bf16 v[74:77], v[166:169], v[210:213], v[74:77]
	s_setprio 0
	s_barrier
	s_add_i32 s33, s33, s39
	s_mov_b32 m0, s33
	ds_read_b128 v[182:185], v160 offset:16384
	ds_read_b128 v[186:189], v160 offset:17408
	ds_read_b128 v[190:193], v160 offset:18432
	ds_read_b128 v[194:197], v160 offset:19456
	ds_read_b128 v[198:201], v160 offset:20480
	ds_read_b128 v[206:209], v160 offset:21504
	ds_read_b128 v[210:213], v160 offset:22528
	ds_read_b128 v[214:217], v160 offset:23552
	global_load_lds_dwordx4 v0, s[28:29]
	s_add_i32 m0, s33, 0x2000
	s_add_u32 s100, s30, 0x80
	s_addc_u32 s101, s31, 0
	s_add_u32 s56, s28, 0x80000
	s_addc_u32 s57, s29, 0
	s_add_i32 s33, s58, s39
	global_load_lds_dwordx4 v14, s[28:29]
	s_mov_b32 m0, s33
	s_nop 0
	global_load_lds_dwordx4 v0, s[56:57]
	s_add_i32 m0, s33, 0x2000
	s_nop 0
	global_load_lds_dwordx4 v14, s[56:57]
	s_mov_b32 m0, s41
	s_nop 0
	global_load_lds_dwordx4 v136, s[30:31]
	s_mov_b32 m0, s42
	s_nop 0
	global_load_lds_dwordx4 v134, s[30:31]
	s_waitcnt vmcnt(8)
	s_waitcnt lgkmcnt(0)
	s_barrier
; #define PG8_STAGE(bufoff, gbase, voff) do { _Pragma("unroll") for (int _i = 0; _i < 2; ++_i) \
;         __builtin_amdgcn_global_load_lds((const unsigned*)((const char*)(gbase) + (voff)[_i]), (PG8_LAS unsigned*)(lds + (bufoff) + ldsw + _i * 8192), 16, 0, 0); } while (0)
; #define PG8_LDA(dst, b, h) do { _Pragma("unroll") for (int m = 0; m < 4; ++m) _Pragma("unroll") for (int k = 0; k < 2; ++k) dst[m][k] = *(const PG8_LAS bf16x8*)(lds + PG8_SA(b, h) + aoff + m * 2048 + k * 1024); } while (0)
; #define PG8_LDB(dst, b, h) do { _Pragma("unroll") for (int n = 0; n < 2; ++n) _Pragma("unroll") for (int k = 0; k < 2; ++k) dst[n][k] = *(const PG8_LAS bf16x8*)(lds + PG8_SB(b, h) + boff + n * 2048 + k * 1024); } while (0)
; #define PG8_MMA(ai, bj, At, Bt) do { __builtin_amdgcn_s_setprio(1); _Pragma("unroll") for (int m = 0; m < 4; ++m) _Pragma("unroll") for (int n = 0; n < 2; ++n) _Pragma("unroll") for (int k = 0; k < 2; ++k) \
;         acc[ai][bj][m][n] = __builtin_amdgcn_mfma_f32_16x16x32_bf16(Bt[n][k], At[m][k], acc[ai][bj][m][n], 0, 0, 0); __builtin_amdgcn_s_setprio(0); } while (0)
; #define PG8_WAIT_V(n) asm volatile("s_waitcnt vmcnt(" #n ")" ::: "memory")
; #define PG8_WAIT_L(n) asm volatile("s_waitcnt lgkmcnt(" #n ")" ::: "memory")
; #define PG8_BAR __builtin_amdgcn_s_barrier()
; #define PG8_SCHED __builtin_amdgcn_sched_barrier(0)
; template <class Epi, class Sched, bool ALIGN_EPI = false, bool SP2 = false>
; __device__ __forceinline__ void gemm_phase(PG8_LAS unsigned char* lds, const Gemm g, const Sched& S, const Epi& E) {
;     ...
;             PG8_WAIT_V(8); PG8_WAIT_L(0); PG8_BAR; PG8_MMA(1, 0, At, B0); PG8_MMA(1, 1, At, B1); PG8_BAR; PG8_SCHED;
;             PG8_LDB(B0, 1, 0); PG8_LDB(B1, 1, 1); PG8_SCHED; PG8_LDA(At, 1, 0); PG8_STAGE(PG8_SA(0, 1), a2 + hstep, voffA);
;             PG8_WAIT_V(8); PG8_WAIT_L(0); PG8_BAR; PG8_MMA(0, 0, At, B0); PG8_MMA(0, 1, At, B1); PG8_BAR; PG8_SCHED;
	s_setprio 1
	s_waitcnt lgkmcnt(0)
	v_mfma_f32_16x16x32_bf16 v[66:69], v[142:145], v[182:185], 0
	v_mfma_f32_16x16x32_bf16 v[66:69], v[146:149], v[186:189], v[66:69]
	v_mfma_f32_16x16x32_bf16 v[62:65], v[162:165], v[186:189], 0
	v_mfma_f32_16x16x32_bf16 v[62:65], v[150:153], v[182:185], v[62:65]
	v_mfma_f32_16x16x32_bf16 v[46:49], v[150:153], v[190:193], 0
	v_mfma_f32_16x16x32_bf16 v[46:49], v[162:165], v[194:197], v[46:49]
	v_mfma_f32_16x16x32_bf16 v[50:53], v[146:149], v[194:197], 0
	v_mfma_f32_16x16x32_bf16 v[50:53], v[142:145], v[190:193], v[50:53]
	v_mfma_f32_16x16x32_bf16 v[34:37], v[142:145], v[198:201], 0
	v_mfma_f32_16x16x32_bf16 v[34:37], v[146:149], v[206:209], v[34:37]
	v_mfma_f32_16x16x32_bf16 v[30:33], v[162:165], v[206:209], 0
	v_mfma_f32_16x16x32_bf16 v[30:33], v[150:153], v[198:201], v[30:33]
	v_mfma_f32_16x16x32_bf16 v[10:13], v[150:153], v[210:213], 0
	v_mfma_f32_16x16x32_bf16 v[10:13], v[162:165], v[214:217], v[10:13]
	v_mfma_f32_16x16x32_bf16 v[18:21], v[146:149], v[214:217], 0
	v_mfma_f32_16x16x32_bf16 v[18:21], v[142:145], v[210:213], v[18:21]
	s_setprio 0
	s_setprio 1
	v_mfma_f32_16x16x32_bf16 v[58:61], v[166:169], v[182:185], 0
	v_mfma_f32_16x16x32_bf16 v[58:61], v[170:173], v[186:189], v[58:61]
	v_mfma_f32_16x16x32_bf16 v[54:57], v[178:181], v[186:189], 0
	v_mfma_f32_16x16x32_bf16 v[54:57], v[174:177], v[182:185], v[54:57]
	v_mfma_f32_16x16x32_bf16 v[38:41], v[174:177], v[190:193], 0
	v_mfma_f32_16x16x32_bf16 v[38:41], v[178:181], v[194:197], v[38:41]
	v_mfma_f32_16x16x32_bf16 v[42:45], v[170:173], v[194:197], 0
	v_mfma_f32_16x16x32_bf16 v[42:45], v[166:169], v[190:193], v[42:45]
	v_mfma_f32_16x16x32_bf16 v[26:29], v[166:169], v[198:201], 0
	v_mfma_f32_16x16x32_bf16 v[26:29], v[170:173], v[206:209], v[26:29]
	v_mfma_f32_16x16x32_bf16 v[22:25], v[178:181], v[206:209], 0
	v_mfma_f32_16x16x32_bf16 v[22:25], v[174:177], v[198:201], v[22:25]
	v_mfma_f32_16x16x32_bf16 v[2:5], v[174:177], v[210:213], 0
	v_mfma_f32_16x16x32_bf16 v[2:5], v[178:181], v[214:217], v[2:5]
	v_mfma_f32_16x16x32_bf16 v[6:9], v[170:173], v[214:217], 0
	v_mfma_f32_16x16x32_bf16 v[6:9], v[166:169], v[210:213], v[6:9]
	s_setprio 0
	s_barrier
	s_add_i32 s33, 0, 0x18000
	s_add_i32 s56, 0, 0x1c000
	ds_read_b128 v[142:145], v226 offset:32768
	ds_read_b128 v[146:149], v226 offset:33792
	ds_read_b128 v[150:153], v226 offset:34816
	ds_read_b128 v[162:165], v226 offset:35840
	ds_read_b128 v[166:169], v226 offset:49152
	ds_read_b128 v[170:173], v226 offset:50176
	ds_read_b128 v[174:177], v226 offset:51200
	ds_read_b128 v[178:181], v226 offset:52224
	s_add_u32 s30, s30, 0x80000
	s_addc_u32 s31, s31, 0
	s_mov_b32 m0, s43
	ds_read_b128 v[182:185], v160 offset:32768
	ds_read_b128 v[186:189], v160 offset:33792
	ds_read_b128 v[190:193], v160 offset:34816
	ds_read_b128 v[194:197], v160 offset:35840
	ds_read_b128 v[198:201], v160 offset:36864
	ds_read_b128 v[206:209], v160 offset:37888
	ds_read_b128 v[210:213], v160 offset:38912
	ds_read_b128 v[214:217], v160 offset:39936
	global_load_lds_dwordx4 v136, s[30:31]
	s_mov_b32 m0, s44
	s_nop 0
	global_load_lds_dwordx4 v134, s[30:31]
	s_waitcnt vmcnt(8)
	s_waitcnt lgkmcnt(0)
	s_barrier
	s_setprio 1
	s_waitcnt lgkmcnt(0)
	v_mfma_f32_16x16x32_bf16 v[130:133], v[142:145], v[182:185], v[130:133]
	v_mfma_f32_16x16x32_bf16 v[130:133], v[146:149], v[186:189], v[130:133]
	v_mfma_f32_16x16x32_bf16 v[126:129], v[162:165], v[186:189], v[126:129]
	v_mfma_f32_16x16x32_bf16 v[126:129], v[150:153], v[182:185], v[126:129]
	v_mfma_f32_16x16x32_bf16 v[110:113], v[150:153], v[190:193], v[110:113]
	v_mfma_f32_16x16x32_bf16 v[110:113], v[162:165], v[194:197], v[110:113]
	v_mfma_f32_16x16x32_bf16 v[114:117], v[146:149], v[194:197], v[114:117]
	v_mfma_f32_16x16x32_bf16 v[114:117], v[142:145], v[190:193], v[114:117]
	v_mfma_f32_16x16x32_bf16 v[98:101], v[142:145], v[198:201], v[98:101]
	v_mfma_f32_16x16x32_bf16 v[98:101], v[146:149], v[206:209], v[98:101]
	v_mfma_f32_16x16x32_bf16 v[94:97], v[162:165], v[206:209], v[94:97]
	v_mfma_f32_16x16x32_bf16 v[94:97], v[150:153], v[198:201], v[94:97]
	v_mfma_f32_16x16x32_bf16 v[78:81], v[150:153], v[210:213], v[78:81]
	v_mfma_f32_16x16x32_bf16 v[78:81], v[162:165], v[214:217], v[78:81]
	v_mfma_f32_16x16x32_bf16 v[82:85], v[146:149], v[214:217], v[82:85]
	v_mfma_f32_16x16x32_bf16 v[82:85], v[142:145], v[210:213], v[82:85]
	s_setprio 0
	s_setprio 1
	v_mfma_f32_16x16x32_bf16 v[122:125], v[166:169], v[182:185], v[122:125]
	v_mfma_f32_16x16x32_bf16 v[122:125], v[170:173], v[186:189], v[122:125]
	v_mfma_f32_16x16x32_bf16 v[118:121], v[178:181], v[186:189], v[118:121]
	v_mfma_f32_16x16x32_bf16 v[118:121], v[174:177], v[182:185], v[118:121]
	v_mfma_f32_16x16x32_bf16 v[102:105], v[174:177], v[190:193], v[102:105]
	v_mfma_f32_16x16x32_bf16 v[102:105], v[178:181], v[194:197], v[102:105]
	v_mfma_f32_16x16x32_bf16 v[106:109], v[170:173], v[194:197], v[106:109]
	v_mfma_f32_16x16x32_bf16 v[106:109], v[166:169], v[190:193], v[106:109]
	v_mfma_f32_16x16x32_bf16 v[90:93], v[166:169], v[198:201], v[90:93]
	v_mfma_f32_16x16x32_bf16 v[90:93], v[170:173], v[206:209], v[90:93]
	v_mfma_f32_16x16x32_bf16 v[86:89], v[178:181], v[206:209], v[86:89]
	v_mfma_f32_16x16x32_bf16 v[86:89], v[174:177], v[198:201], v[86:89]
	v_mfma_f32_16x16x32_bf16 v[70:73], v[174:177], v[210:213], v[70:73]
	v_mfma_f32_16x16x32_bf16 v[70:73], v[178:181], v[214:217], v[70:73]
	v_mfma_f32_16x16x32_bf16 v[74:77], v[170:173], v[214:217], v[74:77]
	v_mfma_f32_16x16x32_bf16 v[74:77], v[166:169], v[210:213], v[74:77]
	s_setprio 0
	s_barrier
; #define PG8_STAGE(bufoff, gbase, voff) do { _Pragma("unroll") for (int _i = 0; _i < 2; ++_i) \
;         __builtin_amdgcn_global_load_lds((const unsigned*)((const char*)(gbase) + (voff)[_i]), (PG8_LAS unsigned*)(lds + (bufoff) + ldsw + _i * 8192), 16, 0, 0); } while (0)
; #define PG8_LDA(dst, b, h) do { _Pragma("unroll") for (int m = 0; m < 4; ++m) _Pragma("unroll") for (int k = 0; k < 2; ++k) dst[m][k] = *(const PG8_LAS bf16x8*)(lds + PG8_SA(b, h) + aoff + m * 2048 + k * 1024); } while (0)
; #define PG8_LDB(dst, b, h) do { _Pragma("unroll") for (int n = 0; n < 2; ++n) _Pragma("unroll") for (int k = 0; k < 2; ++k) dst[n][k] = *(const PG8_LAS bf16x8*)(lds + PG8_SB(b, h) + boff + n * 2048 + k * 1024); } while (0)
; #define PG8_MMA(ai, bj, At, Bt) do { __builtin_amdgcn_s_setprio(1); _Pragma("unroll") for (int m = 0; m < 4; ++m) _Pragma("unroll") for (int n = 0; n < 2; ++n) _Pragma("unroll") for (int k = 0; k < 2; ++k) \
;         acc[ai][bj][m][n] = __builtin_amdgcn_mfma_f32_16x16x32_bf16(Bt[n][k], At[m][k], acc[ai][bj][m][n], 0, 0, 0); __builtin_amdgcn_s_setprio(0); } while (0)
; #define PG8_WAIT_V(n) asm volatile("s_waitcnt vmcnt(" #n ")" ::: "memory")
; template <class Epi, class Sched, bool ALIGN_EPI = false, bool SP2 = false>
; __device__ __forceinline__ void gemm_phase(PG8_LAS unsigned char* lds, const Gemm g, const Sched& S, const Epi& E) {
;     ...
;             PG8_LDB(B0, 0, 0); PG8_LDB(B1, 0, 1); PG8_SCHED; PG8_LDA(At, 0, 0); PG8_STAGE(PG8_SA(1, 1), a1 + hstep, voffA);
;             PG8_WAIT_V(8); PG8_WAIT_L(0); PG8_BAR; PG8_MMA(0, 0, At, B0); PG8_MMA(0, 1, At, B1); PG8_BAR; PG8_SCHED;
;             PG8_LDA(At, 0, 1); PG8_STAGE(PG8_SB(0, 0), b2, voffB); PG8_STAGE(PG8_SB(0, 1), b2 + hstep, voffB); PG8_STAGE(PG8_SA(0, 0), a2, voffA);
;             PG8_WAIT_V(8); PG8_WAIT_L(0); PG8_BAR; PG8_MMA(1, 0, At, B0); PG8_MMA(1, 1, At, B1); PG8_BAR; PG8_SCHED;
;             PG8_LDB(B0, 1, 0); PG8_LDB(B1, 1, 1); PG8_SCHED; PG8_LDA(At, 1, 0); PG8_STAGE(PG8_SA(0, 1), a2 + hstep, voffA);
;             PG8_WAIT_V(8); PG8_WAIT_L(0); PG8_BAR; PG8_MMA(0, 0, At, B0); PG8_MMA(0, 1, At, B1); PG8_BAR; PG8_SCHED;
;             PG8_LDA(At, 1, 1); PG8_STAGE(PG8_SB(1, 0), b3, voffB); PG8_STAGE(PG8_SB(1, 1), b3 + hstep, voffB); PG8_STAGE(PG8_SA(1, 0), a3, voffA);
;             PG8_WAIT_V(8); PG8_WAIT_L(0); PG8_BAR; PG8_MMA(1, 0, At, B0); PG8_MMA(1, 1, At, B1); PG8_BAR; PG8_SCHED;
	s_add_i32 s30, s33, s39
	s_add_i32 m0, s30, 0xffffff80
	ds_read_b128 v[182:185], v160 offset:49152
	ds_read_b128 v[186:189], v160 offset:50176
	ds_read_b128 v[190:193], v160 offset:51200
	ds_read_b128 v[194:197], v160 offset:52224
	ds_read_b128 v[198:201], v160 offset:53248
	ds_read_b128 v[206:209], v160 offset:54272
	ds_read_b128 v[210:213], v160 offset:55296
	ds_read_b128 v[214:217], v160 offset:56320
	global_load_lds_dwordx4 v0, s[28:29] offset:128
	s_add_i32 m0, s30, 0x1f80
	s_add_i32 s30, s56, s39
	global_load_lds_dwordx4 v14, s[28:29] offset:128
	s_add_u32 s28, s28, 0x80080
	s_addc_u32 s29, s29, 0
	s_mov_b32 m0, s30
	s_nop 0
	global_load_lds_dwordx4 v0, s[28:29]
	s_add_i32 m0, s30, 0x2000
	s_nop 0
	global_load_lds_dwordx4 v14, s[28:29]
	s_mov_b32 m0, s46
	s_nop 0
	global_load_lds_dwordx4 v136, s[100:101]
	s_mov_b32 m0, s47
	s_nop 0
	global_load_lds_dwordx4 v134, s[100:101]
	s_waitcnt vmcnt(8)
	s_waitcnt lgkmcnt(0)
	s_barrier
	s_setprio 1
	s_waitcnt lgkmcnt(0)
	v_mfma_f32_16x16x32_bf16 v[66:69], v[142:145], v[182:185], v[66:69]
	v_mfma_f32_16x16x32_bf16 v[66:69], v[146:149], v[186:189], v[66:69]
	v_mfma_f32_16x16x32_bf16 v[62:65], v[162:165], v[186:189], v[62:65]
	v_mfma_f32_16x16x32_bf16 v[62:65], v[150:153], v[182:185], v[62:65]
	v_mfma_f32_16x16x32_bf16 v[46:49], v[150:153], v[190:193], v[46:49]
	v_mfma_f32_16x16x32_bf16 v[46:49], v[162:165], v[194:197], v[46:49]
	v_mfma_f32_16x16x32_bf16 v[50:53], v[146:149], v[194:197], v[50:53]
	v_mfma_f32_16x16x32_bf16 v[50:53], v[142:145], v[190:193], v[50:53]
	v_mfma_f32_16x16x32_bf16 v[34:37], v[142:145], v[198:201], v[34:37]
	v_mfma_f32_16x16x32_bf16 v[34:37], v[146:149], v[206:209], v[34:37]
	v_mfma_f32_16x16x32_bf16 v[30:33], v[162:165], v[206:209], v[30:33]
	v_mfma_f32_16x16x32_bf16 v[30:33], v[150:153], v[198:201], v[30:33]
	v_mfma_f32_16x16x32_bf16 v[10:13], v[150:153], v[210:213], v[10:13]
	v_mfma_f32_16x16x32_bf16 v[10:13], v[162:165], v[214:217], v[10:13]
	v_mfma_f32_16x16x32_bf16 v[18:21], v[146:149], v[214:217], v[18:21]
	v_mfma_f32_16x16x32_bf16 v[18:21], v[142:145], v[210:213], v[18:21]
	s_setprio 0
	s_setprio 1
	v_mfma_f32_16x16x32_bf16 v[58:61], v[166:169], v[182:185], v[58:61]
	v_mfma_f32_16x16x32_bf16 v[58:61], v[170:173], v[186:189], v[58:61]
	v_mfma_f32_16x16x32_bf16 v[54:57], v[178:181], v[186:189], v[54:57]
	v_mfma_f32_16x16x32_bf16 v[54:57], v[174:177], v[182:185], v[54:57]
	v_mfma_f32_16x16x32_bf16 v[38:41], v[174:177], v[190:193], v[38:41]
	v_mfma_f32_16x16x32_bf16 v[38:41], v[178:181], v[194:197], v[38:41]
	v_mfma_f32_16x16x32_bf16 v[42:45], v[170:173], v[194:197], v[42:45]
	v_mfma_f32_16x16x32_bf16 v[42:45], v[166:169], v[190:193], v[42:45]
	v_mfma_f32_16x16x32_bf16 v[26:29], v[166:169], v[198:201], v[26:29]
	v_mfma_f32_16x16x32_bf16 v[26:29], v[170:173], v[206:209], v[26:29]
	v_mfma_f32_16x16x32_bf16 v[22:25], v[178:181], v[206:209], v[22:25]
	v_mfma_f32_16x16x32_bf16 v[22:25], v[174:177], v[198:201], v[22:25]
	v_mfma_f32_16x16x32_bf16 v[2:5], v[174:177], v[210:213], v[2:5]
	v_mfma_f32_16x16x32_bf16 v[2:5], v[178:181], v[214:217], v[2:5]
	v_mfma_f32_16x16x32_bf16 v[6:9], v[170:173], v[214:217], v[6:9]
	v_mfma_f32_16x16x32_bf16 v[6:9], v[166:169], v[210:213], v[6:9]
	s_setprio 0
	s_barrier
	s_add_i32 s55, s55, 2
	s_add_u32 s53, s53, 0x100
	s_addc_u32 s54, s54, 0
	s_add_u32 s26, s26, 0x100
	s_addc_u32 s27, s27, 0
	s_cmp_gt_u32 s55, 29
.LBB0_373:
	s_add_u32 s28, s26, 0xfff80080
	s_addc_u32 s29, s27, -1
	s_add_i32 s33, 0, 0x10000
	s_cmp_eq_u32 s55, 28
	s_cselect_b32 s31, s5, s29
	s_cselect_b32 s30, s11, s28
	s_cselect_b32 s29, s19, s54
	s_cselect_b32 s28, s21, s53
	s_add_i32 s58, 0, 0x14000
	ds_read_b128 v[142:145], v226
	ds_read_b128 v[146:149], v226 offset:1024
	ds_read_b128 v[150:153], v226 offset:2048
	ds_read_b128 v[162:165], v226 offset:3072
	ds_read_b128 v[166:169], v226 offset:16384
	ds_read_b128 v[170:173], v226 offset:17408
	ds_read_b128 v[174:177], v226 offset:18432
	ds_read_b128 v[178:181], v226 offset:19456
	s_add_i32 m0, s41, 0xc000
	ds_read_b128 v[182:185], v160
	ds_read_b128 v[186:189], v160 offset:1024
	ds_read_b128 v[190:193], v160 offset:2048
	ds_read_b128 v[194:197], v160 offset:3072
	ds_read_b128 v[198:201], v160 offset:4096
	ds_read_b128 v[206:209], v160 offset:5120
	ds_read_b128 v[210:213], v160 offset:6144
	ds_read_b128 v[214:217], v160 offset:7168
	global_load_lds_dwordx4 v140, s[26:27]
	s_add_i32 m0, s41, 0xe000
	s_nop 0
	global_load_lds_dwordx4 v138, s[26:27]
	s_waitcnt vmcnt(8)
	s_waitcnt lgkmcnt(0)
	s_barrier
; #define PG8_STAGE(bufoff, gbase, voff) do { _Pragma("unroll") for (int _i = 0; _i < 2; ++_i) \
;         __builtin_amdgcn_global_load_lds((const unsigned*)((const char*)(gbase) + (voff)[_i]), (PG8_LAS unsigned*)(lds + (bufoff) + ldsw + _i * 8192), 16, 0, 0); } while (0)
; #define PG8_LDA(dst, b, h) do { _Pragma("unroll") for (int m = 0; m < 4; ++m) _Pragma("unroll") for (int k = 0; k < 2; ++k) dst[m][k] = *(const PG8_LAS bf16x8*)(lds + PG8_SA(b, h) + aoff + m * 2048 + k * 1024); } while (0)
; #define PG8_MMA(ai, bj, At, Bt) do { __builtin_amdgcn_s_setprio(1); _Pragma("unroll") for (int m = 0; m < 4; ++m) _Pragma("unroll") for (int n = 0; n < 2; ++n) _Pragma("unroll") for (int k = 0; k < 2; ++k) \
;         acc[ai][bj][m][n] = __builtin_amdgcn_mfma_f32_16x16x32_bf16(Bt[n][k], At[m][k], acc[ai][bj][m][n], 0, 0, 0); __builtin_amdgcn_s_setprio(0); } while (0)
; #define PG8_WAIT_V(n) asm volatile("s_waitcnt vmcnt(" #n ")" ::: "memory")
; #define PG8_WAIT_L(n) asm volatile("s_waitcnt lgkmcnt(" #n ")" ::: "memory")
; #define PG8_BAR __builtin_amdgcn_s_barrier()
; #define PG8_SCHED __builtin_amdgcn_sched_barrier(0)
; template <class Epi, class Sched, bool ALIGN_EPI = false, bool SP2 = false>
; __device__ __forceinline__ void gemm_phase(PG8_LAS unsigned char* lds, const Gemm g, const Sched& S, const Epi& E) {
;     ...
;             PG8_WAIT_V(8); PG8_WAIT_L(0); PG8_BAR; PG8_MMA(0, 0, At, B0); PG8_MMA(0, 1, At, B1); PG8_BAR; PG8_SCHED;
;             PG8_LDA(At, 0, 1); PG8_STAGE(PG8_SB(0, 0), b2, voffB); PG8_STAGE(PG8_SB(0, 1), b2 + hstep, voffB); PG8_STAGE(PG8_SA(0, 0), a2, voffA);
;             PG8_WAIT_V(8); PG8_WAIT_L(0); PG8_BAR; PG8_MMA(1, 0, At, B0); PG8_MMA(1, 1, At, B1); PG8_BAR; PG8_SCHED;
	s_setprio 1
	s_waitcnt lgkmcnt(0)
	v_mfma_f32_16x16x32_bf16 v[130:133], v[142:145], v[182:185], v[130:133]
	v_mfma_f32_16x16x32_bf16 v[130:133], v[146:149], v[186:189], v[130:133]
	v_mfma_f32_16x16x32_bf16 v[126:129], v[162:165], v[186:189], v[126:129]
	v_mfma_f32_16x16x32_bf16 v[126:129], v[150:153], v[182:185], v[126:129]
	v_mfma_f32_16x16x32_bf16 v[110:113], v[150:153], v[190:193], v[110:113]
	v_mfma_f32_16x16x32_bf16 v[110:113], v[162:165], v[194:197], v[110:113]
	v_mfma_f32_16x16x32_bf16 v[114:117], v[146:149], v[194:197], v[114:117]
	v_mfma_f32_16x16x32_bf16 v[114:117], v[142:145], v[190:193], v[114:117]
	v_mfma_f32_16x16x32_bf16 v[98:101], v[142:145], v[198:201], v[98:101]
	v_mfma_f32_16x16x32_bf16 v[98:101], v[146:149], v[206:209], v[98:101]
	v_mfma_f32_16x16x32_bf16 v[94:97], v[162:165], v[206:209], v[94:97]
	v_mfma_f32_16x16x32_bf16 v[94:97], v[150:153], v[198:201], v[94:97]
	v_mfma_f32_16x16x32_bf16 v[78:81], v[150:153], v[210:213], v[78:81]
	v_mfma_f32_16x16x32_bf16 v[78:81], v[162:165], v[214:217], v[78:81]
	v_mfma_f32_16x16x32_bf16 v[82:85], v[146:149], v[214:217], v[82:85]
	v_mfma_f32_16x16x32_bf16 v[82:85], v[142:145], v[210:213], v[82:85]
	s_setprio 0
	s_setprio 1
	v_mfma_f32_16x16x32_bf16 v[122:125], v[166:169], v[182:185], v[122:125]
	v_mfma_f32_16x16x32_bf16 v[122:125], v[170:173], v[186:189], v[122:125]
	v_mfma_f32_16x16x32_bf16 v[118:121], v[178:181], v[186:189], v[118:121]
	v_mfma_f32_16x16x32_bf16 v[118:121], v[174:177], v[182:185], v[118:121]
	v_mfma_f32_16x16x32_bf16 v[102:105], v[174:177], v[190:193], v[102:105]
	v_mfma_f32_16x16x32_bf16 v[102:105], v[178:181], v[194:197], v[102:105]
	v_mfma_f32_16x16x32_bf16 v[106:109], v[170:173], v[194:197], v[106:109]
	v_mfma_f32_16x16x32_bf16 v[106:109], v[166:169], v[190:193], v[106:109]
	v_mfma_f32_16x16x32_bf16 v[90:93], v[166:169], v[198:201], v[90:93]
	v_mfma_f32_16x16x32_bf16 v[90:93], v[170:173], v[206:209], v[90:93]
	v_mfma_f32_16x16x32_bf16 v[86:89], v[178:181], v[206:209], v[86:89]
	v_mfma_f32_16x16x32_bf16 v[86:89], v[174:177], v[198:201], v[86:89]
	v_mfma_f32_16x16x32_bf16 v[70:73], v[174:177], v[210:213], v[70:73]
	v_mfma_f32_16x16x32_bf16 v[70:73], v[178:181], v[214:217], v[70:73]
	v_mfma_f32_16x16x32_bf16 v[74:77], v[170:173], v[214:217], v[74:77]
	v_mfma_f32_16x16x32_bf16 v[74:77], v[166:169], v[210:213], v[74:77]
	s_setprio 0
	s_barrier
	s_add_i32 s33, s33, s39
	s_mov_b32 m0, s33
	ds_read_b128 v[182:185], v160 offset:16384
	ds_read_b128 v[186:189], v160 offset:17408
	ds_read_b128 v[190:193], v160 offset:18432
	ds_read_b128 v[194:197], v160 offset:19456
	ds_read_b128 v[198:201], v160 offset:20480
	ds_read_b128 v[206:209], v160 offset:21504
	ds_read_b128 v[210:213], v160 offset:22528
	ds_read_b128 v[214:217], v160 offset:23552
	global_load_lds_dwordx4 v0, s[28:29]
	s_add_i32 m0, s33, 0x2000
	s_add_u32 s100, s30, 0x80
	s_addc_u32 s101, s31, 0
	s_add_u32 s56, s28, 0x80000
	s_addc_u32 s57, s29, 0
	s_add_i32 s33, s58, s39
	global_load_lds_dwordx4 v14, s[28:29]
	s_mov_b32 m0, s33
	s_nop 0
	global_load_lds_dwordx4 v0, s[56:57]
	s_add_i32 m0, s33, 0x2000
	s_nop 0
	global_load_lds_dwordx4 v14, s[56:57]
	s_mov_b32 m0, s41
	s_nop 0
	global_load_lds_dwordx4 v136, s[30:31]
	s_mov_b32 m0, s42
	s_nop 0
	global_load_lds_dwordx4 v134, s[30:31]
	s_waitcnt vmcnt(8)
	s_waitcnt lgkmcnt(0)
	s_barrier
	s_setprio 1
	s_waitcnt lgkmcnt(0)
	v_mfma_f32_16x16x32_bf16 v[66:69], v[142:145], v[182:185], v[66:69]
	v_mfma_f32_16x16x32_bf16 v[66:69], v[146:149], v[186:189], v[66:69]
	v_mfma_f32_16x16x32_bf16 v[62:65], v[162:165], v[186:189], v[62:65]
	v_mfma_f32_16x16x32_bf16 v[62:65], v[150:153], v[182:185], v[62:65]
	v_mfma_f32_16x16x32_bf16 v[46:49], v[150:153], v[190:193], v[46:49]
	v_mfma_f32_16x16x32_bf16 v[46:49], v[162:165], v[194:197], v[46:49]
	v_mfma_f32_16x16x32_bf16 v[50:53], v[146:149], v[194:197], v[50:53]
	v_mfma_f32_16x16x32_bf16 v[50:53], v[142:145], v[190:193], v[50:53]
	v_mfma_f32_16x16x32_bf16 v[34:37], v[142:145], v[198:201], v[34:37]
	v_mfma_f32_16x16x32_bf16 v[34:37], v[146:149], v[206:209], v[34:37]
	v_mfma_f32_16x16x32_bf16 v[30:33], v[162:165], v[206:209], v[30:33]
	v_mfma_f32_16x16x32_bf16 v[30:33], v[150:153], v[198:201], v[30:33]
	v_mfma_f32_16x16x32_bf16 v[10:13], v[150:153], v[210:213], v[10:13]
	v_mfma_f32_16x16x32_bf16 v[10:13], v[162:165], v[214:217], v[10:13]
	v_mfma_f32_16x16x32_bf16 v[18:21], v[146:149], v[214:217], v[18:21]
	v_mfma_f32_16x16x32_bf16 v[18:21], v[142:145], v[210:213], v[18:21]
	s_setprio 0
	s_setprio 1
	v_mfma_f32_16x16x32_bf16 v[58:61], v[166:169], v[182:185], v[58:61]
	v_mfma_f32_16x16x32_bf16 v[58:61], v[170:173], v[186:189], v[58:61]
	v_mfma_f32_16x16x32_bf16 v[54:57], v[178:181], v[186:189], v[54:57]
	v_mfma_f32_16x16x32_bf16 v[54:57], v[174:177], v[182:185], v[54:57]
	v_mfma_f32_16x16x32_bf16 v[38:41], v[174:177], v[190:193], v[38:41]
	v_mfma_f32_16x16x32_bf16 v[38:41], v[178:181], v[194:197], v[38:41]
	v_mfma_f32_16x16x32_bf16 v[42:45], v[170:173], v[194:197], v[42:45]
	v_mfma_f32_16x16x32_bf16 v[42:45], v[166:169], v[190:193], v[42:45]
	v_mfma_f32_16x16x32_bf16 v[26:29], v[166:169], v[198:201], v[26:29]
	v_mfma_f32_16x16x32_bf16 v[26:29], v[170:173], v[206:209], v[26:29]
	v_mfma_f32_16x16x32_bf16 v[22:25], v[178:181], v[206:209], v[22:25]
	v_mfma_f32_16x16x32_bf16 v[22:25], v[174:177], v[198:201], v[22:25]
	v_mfma_f32_16x16x32_bf16 v[2:5], v[174:177], v[210:213], v[2:5]
	v_mfma_f32_16x16x32_bf16 v[2:5], v[178:181], v[214:217], v[2:5]
	v_mfma_f32_16x16x32_bf16 v[6:9], v[170:173], v[214:217], v[6:9]
	v_mfma_f32_16x16x32_bf16 v[6:9], v[166:169], v[210:213], v[6:9]
	s_setprio 0
	s_barrier
; #define PG8_STAGE(bufoff, gbase, voff) do { _Pragma("unroll") for (int _i = 0; _i < 2; ++_i) \
;         __builtin_amdgcn_global_load_lds((const unsigned*)((const char*)(gbase) + (voff)[_i]), (PG8_LAS unsigned*)(lds + (bufoff) + ldsw + _i * 8192), 16, 0, 0); } while (0)
; #define PG8_LDA(dst, b, h) do { _Pragma("unroll") for (int m = 0; m < 4; ++m) _Pragma("unroll") for (int k = 0; k < 2; ++k) dst[m][k] = *(const PG8_LAS bf16x8*)(lds + PG8_SA(b, h) + aoff + m * 2048 + k * 1024); } while (0)
; #define PG8_LDB(dst, b, h) do { _Pragma("unroll") for (int n = 0; n < 2; ++n) _Pragma("unroll") for (int k = 0; k < 2; ++k) dst[n][k] = *(const PG8_LAS bf16x8*)(lds + PG8_SB(b, h) + boff + n * 2048 + k * 1024); } while (0)
; #define PG8_MMA(ai, bj, At, Bt) do { __builtin_amdgcn_s_setprio(1); _Pragma("unroll") for (int m = 0; m < 4; ++m) _Pragma("unroll") for (int n = 0; n < 2; ++n) _Pragma("unroll") for (int k = 0; k < 2; ++k) \
;         acc[ai][bj][m][n] = __builtin_amdgcn_mfma_f32_16x16x32_bf16(Bt[n][k], At[m][k], acc[ai][bj][m][n], 0, 0, 0); __builtin_amdgcn_s_setprio(0); } while (0)
; #define PG8_WAIT_V(n) asm volatile("s_waitcnt vmcnt(" #n ")" ::: "memory")
; #define PG8_WAIT_L(n) asm volatile("s_waitcnt lgkmcnt(" #n ")" ::: "memory")
; #define PG8_BAR __builtin_amdgcn_s_barrier()
; #define PG8_SCHED __builtin_amdgcn_sched_barrier(0)
; template <class Epi, class Sched, bool ALIGN_EPI = false, bool SP2 = false>
; __device__ __forceinline__ void gemm_phase(PG8_LAS unsigned char* lds, const Gemm g, const Sched& S, const Epi& E) {
;     ...
;             PG8_LDB(B0, 1, 0); PG8_LDB(B1, 1, 1); PG8_SCHED; PG8_LDA(At, 1, 0); PG8_STAGE(PG8_SA(0, 1), a2 + hstep, voffA);
;             PG8_WAIT_V(8); PG8_WAIT_L(0); PG8_BAR; PG8_MMA(0, 0, At, B0); PG8_MMA(0, 1, At, B1); PG8_BAR; PG8_SCHED;
;             PG8_LDA(At, 1, 1); PG8_STAGE(PG8_SB(1, 0), b3, voffB); PG8_STAGE(PG8_SB(1, 1), b3 + hstep, voffB); PG8_STAGE(PG8_SA(1, 0), a3, voffA);
;             PG8_WAIT_V(8); PG8_WAIT_L(0); PG8_BAR; PG8_MMA(1, 0, At, B0); PG8_MMA(1, 1, At, B1); PG8_BAR; PG8_SCHED;
;     ...
;         if constexpr (ALIGN_EPI) { if (wr == 0) PG8_BAR; }
	s_add_i32 s33, 0, 0x18000
	s_add_i32 s56, 0, 0x1c000
	ds_read_b128 v[142:145], v226 offset:32768
	ds_read_b128 v[146:149], v226 offset:33792
	ds_read_b128 v[150:153], v226 offset:34816
	ds_read_b128 v[162:165], v226 offset:35840
	ds_read_b128 v[166:169], v226 offset:49152
	ds_read_b128 v[170:173], v226 offset:50176
	ds_read_b128 v[174:177], v226 offset:51200
	ds_read_b128 v[178:181], v226 offset:52224
	s_add_u32 s30, s30, 0x80000
	s_addc_u32 s31, s31, 0
	s_mov_b32 m0, s43
	ds_read_b128 v[182:185], v160 offset:32768
	ds_read_b128 v[186:189], v160 offset:33792
	ds_read_b128 v[190:193], v160 offset:34816
	ds_read_b128 v[194:197], v160 offset:35840
	ds_read_b128 v[198:201], v160 offset:36864
	ds_read_b128 v[206:209], v160 offset:37888
	ds_read_b128 v[210:213], v160 offset:38912
	ds_read_b128 v[214:217], v160 offset:39936
	global_load_lds_dwordx4 v136, s[30:31]
	s_mov_b32 m0, s44
	s_nop 0
	global_load_lds_dwordx4 v134, s[30:31]
	s_waitcnt vmcnt(8)
	s_waitcnt lgkmcnt(0)
	s_barrier
	s_setprio 1
	s_waitcnt lgkmcnt(0)
	v_mfma_f32_16x16x32_bf16 v[130:133], v[142:145], v[182:185], v[130:133]
	v_mfma_f32_16x16x32_bf16 v[130:133], v[146:149], v[186:189], v[130:133]
	v_mfma_f32_16x16x32_bf16 v[126:129], v[162:165], v[186:189], v[126:129]
	v_mfma_f32_16x16x32_bf16 v[126:129], v[150:153], v[182:185], v[126:129]
	v_mfma_f32_16x16x32_bf16 v[110:113], v[150:153], v[190:193], v[110:113]
	v_mfma_f32_16x16x32_bf16 v[110:113], v[162:165], v[194:197], v[110:113]
	v_mfma_f32_16x16x32_bf16 v[114:117], v[146:149], v[194:197], v[114:117]
	v_mfma_f32_16x16x32_bf16 v[114:117], v[142:145], v[190:193], v[114:117]
	v_mfma_f32_16x16x32_bf16 v[98:101], v[142:145], v[198:201], v[98:101]
	v_mfma_f32_16x16x32_bf16 v[98:101], v[146:149], v[206:209], v[98:101]
	v_mfma_f32_16x16x32_bf16 v[94:97], v[162:165], v[206:209], v[94:97]
	v_mfma_f32_16x16x32_bf16 v[94:97], v[150:153], v[198:201], v[94:97]
	v_mfma_f32_16x16x32_bf16 v[78:81], v[150:153], v[210:213], v[78:81]
	v_mfma_f32_16x16x32_bf16 v[78:81], v[162:165], v[214:217], v[78:81]
	v_mfma_f32_16x16x32_bf16 v[82:85], v[146:149], v[214:217], v[82:85]
	v_mfma_f32_16x16x32_bf16 v[82:85], v[142:145], v[210:213], v[82:85]
	s_setprio 0
	s_setprio 1
	v_mfma_f32_16x16x32_bf16 v[122:125], v[166:169], v[182:185], v[122:125]
	v_mfma_f32_16x16x32_bf16 v[122:125], v[170:173], v[186:189], v[122:125]
	v_mfma_f32_16x16x32_bf16 v[118:121], v[178:181], v[186:189], v[118:121]
	v_mfma_f32_16x16x32_bf16 v[118:121], v[174:177], v[182:185], v[118:121]
	v_mfma_f32_16x16x32_bf16 v[102:105], v[174:177], v[190:193], v[102:105]
	v_mfma_f32_16x16x32_bf16 v[102:105], v[178:181], v[194:197], v[102:105]
	v_mfma_f32_16x16x32_bf16 v[106:109], v[170:173], v[194:197], v[106:109]
	v_mfma_f32_16x16x32_bf16 v[106:109], v[166:169], v[190:193], v[106:109]
	v_mfma_f32_16x16x32_bf16 v[90:93], v[166:169], v[198:201], v[90:93]
	v_mfma_f32_16x16x32_bf16 v[90:93], v[170:173], v[206:209], v[90:93]
	v_mfma_f32_16x16x32_bf16 v[86:89], v[178:181], v[206:209], v[86:89]
	v_mfma_f32_16x16x32_bf16 v[86:89], v[174:177], v[198:201], v[86:89]
	v_mfma_f32_16x16x32_bf16 v[70:73], v[174:177], v[210:213], v[70:73]
	v_mfma_f32_16x16x32_bf16 v[70:73], v[178:181], v[214:217], v[70:73]
	v_mfma_f32_16x16x32_bf16 v[74:77], v[170:173], v[214:217], v[74:77]
	v_mfma_f32_16x16x32_bf16 v[74:77], v[166:169], v[210:213], v[74:77]
	s_setprio 0
	s_barrier
	s_add_i32 s30, s33, s39
	s_add_i32 m0, s30, 0xffffff80
	ds_read_b128 v[182:185], v160 offset:49152
	ds_read_b128 v[186:189], v160 offset:50176
	ds_read_b128 v[190:193], v160 offset:51200
	ds_read_b128 v[194:197], v160 offset:52224
	ds_read_b128 v[198:201], v160 offset:53248
	ds_read_b128 v[206:209], v160 offset:54272
	ds_read_b128 v[210:213], v160 offset:55296
	ds_read_b128 v[214:217], v160 offset:56320
	global_load_lds_dwordx4 v0, s[28:29] offset:128
	s_add_i32 m0, s30, 0x1f80
	s_add_i32 s30, s56, s39
	global_load_lds_dwordx4 v14, s[28:29] offset:128
	s_add_u32 s28, s28, 0x80080
	s_addc_u32 s29, s29, 0
	s_mov_b32 m0, s30
	s_nop 0
	global_load_lds_dwordx4 v0, s[28:29]
	s_add_i32 m0, s30, 0x2000
	s_nop 0
	global_load_lds_dwordx4 v14, s[28:29]
	s_mov_b32 m0, s46
	s_nop 0
	global_load_lds_dwordx4 v136, s[100:101]
	s_mov_b32 m0, s47
	s_nop 0
	global_load_lds_dwordx4 v134, s[100:101]
	s_waitcnt vmcnt(8)
	s_waitcnt lgkmcnt(0)
	s_barrier
	s_setprio 1
	s_waitcnt lgkmcnt(0)
	v_mfma_f32_16x16x32_bf16 v[66:69], v[142:145], v[182:185], v[66:69]
	v_mfma_f32_16x16x32_bf16 v[66:69], v[146:149], v[186:189], v[66:69]
	v_mfma_f32_16x16x32_bf16 v[62:65], v[162:165], v[186:189], v[62:65]
	v_mfma_f32_16x16x32_bf16 v[62:65], v[150:153], v[182:185], v[62:65]
	v_mfma_f32_16x16x32_bf16 v[46:49], v[150:153], v[190:193], v[46:49]
	v_mfma_f32_16x16x32_bf16 v[46:49], v[162:165], v[194:197], v[46:49]
	v_mfma_f32_16x16x32_bf16 v[50:53], v[146:149], v[194:197], v[50:53]
	v_mfma_f32_16x16x32_bf16 v[50:53], v[142:145], v[190:193], v[50:53]
	v_mfma_f32_16x16x32_bf16 v[34:37], v[142:145], v[198:201], v[34:37]
	v_mfma_f32_16x16x32_bf16 v[34:37], v[146:149], v[206:209], v[34:37]
	v_mfma_f32_16x16x32_bf16 v[30:33], v[162:165], v[206:209], v[30:33]
	v_mfma_f32_16x16x32_bf16 v[30:33], v[150:153], v[198:201], v[30:33]
	v_mfma_f32_16x16x32_bf16 v[10:13], v[150:153], v[210:213], v[10:13]
	v_mfma_f32_16x16x32_bf16 v[10:13], v[162:165], v[214:217], v[10:13]
	v_mfma_f32_16x16x32_bf16 v[18:21], v[146:149], v[214:217], v[18:21]
	v_mfma_f32_16x16x32_bf16 v[18:21], v[142:145], v[210:213], v[18:21]
	s_setprio 0
	s_setprio 1
	v_mfma_f32_16x16x32_bf16 v[58:61], v[166:169], v[182:185], v[58:61]
	v_mfma_f32_16x16x32_bf16 v[58:61], v[170:173], v[186:189], v[58:61]
	v_mfma_f32_16x16x32_bf16 v[54:57], v[178:181], v[186:189], v[54:57]
	v_mfma_f32_16x16x32_bf16 v[54:57], v[174:177], v[182:185], v[54:57]
	v_mfma_f32_16x16x32_bf16 v[38:41], v[174:177], v[190:193], v[38:41]
	v_mfma_f32_16x16x32_bf16 v[38:41], v[178:181], v[194:197], v[38:41]
	v_mfma_f32_16x16x32_bf16 v[42:45], v[170:173], v[194:197], v[42:45]
	v_mfma_f32_16x16x32_bf16 v[42:45], v[166:169], v[190:193], v[42:45]
	v_mfma_f32_16x16x32_bf16 v[26:29], v[166:169], v[198:201], v[26:29]
	v_mfma_f32_16x16x32_bf16 v[26:29], v[170:173], v[206:209], v[26:29]
	v_mfma_f32_16x16x32_bf16 v[22:25], v[178:181], v[206:209], v[22:25]
	v_mfma_f32_16x16x32_bf16 v[22:25], v[174:177], v[198:201], v[22:25]
	v_mfma_f32_16x16x32_bf16 v[2:5], v[174:177], v[210:213], v[2:5]
	v_mfma_f32_16x16x32_bf16 v[2:5], v[178:181], v[214:217], v[2:5]
	v_mfma_f32_16x16x32_bf16 v[6:9], v[170:173], v[214:217], v[6:9]
	v_mfma_f32_16x16x32_bf16 v[6:9], v[166:169], v[210:213], v[6:9]
	s_setprio 0
	s_barrier
	s_add_i32 s55, s55, 2
	s_add_u32 s53, s53, 0x100
	s_addc_u32 s54, s54, 0
	s_add_u32 s26, s26, 0x100
	s_addc_u32 s27, s27, 0
	s_cmp_gt_u32 s55, 29
	s_cbranch_scc0 .LBB0_373
	s_and_b64 vcc, exec, s[14:15]
	s_cbranch_vccz .LBB0_376
	s_barrier

; #define PG8_STAGE(bufoff, gbase, voff) do { _Pragma("unroll") for (int _i = 0; _i < 2; ++_i) \
;         __builtin_amdgcn_global_load_lds((const unsigned*)((const char*)(gbase) + (voff)[_i]), (PG8_LAS unsigned*)(lds + (bufoff) + ldsw + _i * 8192), 16, 0, 0); } while (0)
; #define PG8_LDA(dst, b, h) do { _Pragma("unroll") for (int m = 0; m < 4; ++m) _Pragma("unroll") for (int k = 0; k < 2; ++k) dst[m][k] = *(const PG8_LAS bf16x8*)(lds + PG8_SA(b, h) + aoff + m * 2048 + k * 1024); } while (0)
; #define PG8_LDB(dst, b, h) do { _Pragma("unroll") for (int n = 0; n < 2; ++n) _Pragma("unroll") for (int k = 0; k < 2; ++k) dst[n][k] = *(const PG8_LAS bf16x8*)(lds + PG8_SB(b, h) + boff + n * 2048 + k * 1024); } while (0)
; #define PG8_WAIT_V(n) asm volatile("s_waitcnt vmcnt(" #n ")" ::: "memory")
; #define PG8_WAIT_L(n) asm volatile("s_waitcnt lgkmcnt(" #n ")" ::: "memory")
; #define PG8_BAR __builtin_amdgcn_s_barrier()
; template <class Epi, class Sched, bool ALIGN_EPI = false, bool SP2 = false>
; __device__ __forceinline__ void gemm_phase(PG8_LAS unsigned char* lds, const Gemm g, const Sched& S, const Epi& E) {
;     ...
;         const bool has_next = S.next(ui + 1, nxt);
;         const char* nA = has_next ? (const char*)g.A + (size_t)nxt.pm * tstep : cA; const char* nB = has_next ? (const char*)g.Bt + (size_t)nxt.pn * tstep : cB;
;         for (int t = 0; t < nt; t += 2) {
;             const bool last = (t == nt - 2);
;             const char* a1 = cA + (size_t)(t + 1) * kstep;
;             const char* a2 = last ? nA : cA + (size_t)(t + 2) * kstep; const char* b2 = last ? nB : cB + (size_t)(t + 2) * kstep;
;             const char* a3 = a2 + kstep; const char* b3 = b2 + kstep;
;             if (last && has_next) S.a_ready(nxt);
;             if constexpr (Epi::MID) { if (t == nt / 2) E.mid(acc, cur, wr, wc, fr, fq); }
;             if constexpr (SP2) {
;             PG8_LDB(B0, 0, 0); PG8_LDB(B1, 0, 1); PG8_SCHED; PG8_LDA(At, 0, 0); PG8_STAGE(PG8_SA(1, 1), a1 + hstep, voffA);
;             PG8_WAIT_V(8); PG8_WAIT_L(0); PG8_BAR; PG8_MMA(0, 0, At, B0); PG8_MMA(0, 1, At, B1); PG8_BAR; PG8_SCHED;
;             PG8_LDA(At, 0, 1); PG8_STAGE(PG8_SB(0, 0), b2, voffB); PG8_STAGE(PG8_SB(0, 1), b2 + hstep, voffB); PG8_STAGE(PG8_SA(0, 0), a2, voffA);
;             PG8_WAIT_V(8); PG8_WAIT_L(0); PG8_BAR; PG8_MMA(1, 0, At, B0); PG8_MMA(1, 1, At, B1); PG8_BAR; PG8_SCHED;
.LBB0_1222:
	s_ashr_i32 s21, s20, 31
	s_lshl_b64 s[22:23], s[20:21], 20
	s_add_u32 s22, s8, s22
	s_addc_u32 s23, s9, s23
	s_and_b64 s[24:25], s[2:3], exec
	s_cselect_b32 s5, s23, s29
	s_cselect_b32 s11, s22, s28
	s_ashr_i32 s19, s18, 31
	s_lshl_b64 s[24:25], s[18:19], 20
	s_add_u32 s24, s36, s24
	s_addc_u32 s25, s37, s25
	s_and_b64 s[30:31], s[2:3], exec
	s_cselect_b32 s19, s25, s27
	s_cselect_b32 s21, s24, s26
	s_add_u32 s54, s26, 0x100
	s_addc_u32 s55, s27, 0
	s_add_u32 s26, s28, 0x80080
	s_addc_u32 s27, s29, 0
	s_mov_b32 s56, -2
	v_add_u32_e32 v226, 0x10000, v155
	s_add_u32 s28, s26, 0xfff80080
	s_addc_u32 s29, s27, -1
	s_add_i32 s33, 0, 0x10000
	s_cmp_eq_u32 s56, 28
	s_cselect_b32 s31, s5, s29
	s_cselect_b32 s30, s11, s28
	s_cselect_b32 s29, s19, s55
	s_cselect_b32 s28, s21, s54
	s_add_i32 s57, 0, 0x14000
	ds_read_b128 v[142:145], v226
	ds_read_b128 v[146:149], v226 offset:1024
	ds_read_b128 v[150:153], v226 offset:2048
	ds_read_b128 v[162:165], v226 offset:3072
	ds_read_b128 v[166:169], v226 offset:16384
	ds_read_b128 v[170:173], v226 offset:17408
	ds_read_b128 v[174:177], v226 offset:18432
	ds_read_b128 v[178:181], v226 offset:19456
	s_add_i32 m0, s42, 0xc000
	ds_read_b128 v[182:185], v160
	ds_read_b128 v[186:189], v160 offset:1024
	ds_read_b128 v[190:193], v160 offset:2048
	ds_read_b128 v[194:197], v160 offset:3072
	ds_read_b128 v[198:201], v160 offset:4096
	ds_read_b128 v[206:209], v160 offset:5120
	ds_read_b128 v[210:213], v160 offset:6144
	ds_read_b128 v[214:217], v160 offset:7168
	global_load_lds_dwordx4 v140, s[26:27]
	s_add_i32 m0, s42, 0xe000
	s_nop 0
	global_load_lds_dwordx4 v138, s[26:27]
	s_waitcnt vmcnt(8)
	s_waitcnt lgkmcnt(0)
	s_barrier
	s_setprio 1
	s_waitcnt lgkmcnt(0)
	v_mfma_f32_16x16x32_bf16 v[130:133], v[142:145], v[182:185], 0
	v_mfma_f32_16x16x32_bf16 v[130:133], v[146:149], v[186:189], v[130:133]
	v_mfma_f32_16x16x32_bf16 v[126:129], v[162:165], v[186:189], 0
	v_mfma_f32_16x16x32_bf16 v[126:129], v[150:153], v[182:185], v[126:129]
	v_mfma_f32_16x16x32_bf16 v[110:113], v[150:153], v[190:193], 0
	v_mfma_f32_16x16x32_bf16 v[110:113], v[162:165], v[194:197], v[110:113]
	v_mfma_f32_16x16x32_bf16 v[114:117], v[146:149], v[194:197], 0
	v_mfma_f32_16x16x32_bf16 v[114:117], v[142:145], v[190:193], v[114:117]
	v_mfma_f32_16x16x32_bf16 v[98:101], v[142:145], v[198:201], 0
	v_mfma_f32_16x16x32_bf16 v[98:101], v[146:149], v[206:209], v[98:101]
	v_mfma_f32_16x16x32_bf16 v[94:97], v[162:165], v[206:209], 0
	v_mfma_f32_16x16x32_bf16 v[94:97], v[150:153], v[198:201], v[94:97]
	v_mfma_f32_16x16x32_bf16 v[78:81], v[150:153], v[210:213], 0
	v_mfma_f32_16x16x32_bf16 v[78:81], v[162:165], v[214:217], v[78:81]
	v_mfma_f32_16x16x32_bf16 v[82:85], v[146:149], v[214:217], 0
	v_mfma_f32_16x16x32_bf16 v[82:85], v[142:145], v[210:213], v[82:85]
	s_setprio 0
	s_setprio 1
	v_mfma_f32_16x16x32_bf16 v[122:125], v[166:169], v[182:185], 0
	v_mfma_f32_16x16x32_bf16 v[122:125], v[170:173], v[186:189], v[122:125]
	v_mfma_f32_16x16x32_bf16 v[118:121], v[178:181], v[186:189], 0
	v_mfma_f32_16x16x32_bf16 v[118:121], v[174:177], v[182:185], v[118:121]
	v_mfma_f32_16x16x32_bf16 v[102:105], v[174:177], v[190:193], 0
	v_mfma_f32_16x16x32_bf16 v[102:105], v[178:181], v[194:197], v[102:105]
	v_mfma_f32_16x16x32_bf16 v[106:109], v[170:173], v[194:197], 0
	v_mfma_f32_16x16x32_bf16 v[106:109], v[166:169], v[190:193], v[106:109]
	v_mfma_f32_16x16x32_bf16 v[90:93], v[166:169], v[198:201], 0
	v_mfma_f32_16x16x32_bf16 v[90:93], v[170:173], v[206:209], v[90:93]
	v_mfma_f32_16x16x32_bf16 v[86:89], v[178:181], v[206:209], 0
	v_mfma_f32_16x16x32_bf16 v[86:89], v[174:177], v[198:201], v[86:89]
	v_mfma_f32_16x16x32_bf16 v[70:73], v[174:177], v[210:213], 0
	v_mfma_f32_16x16x32_bf16 v[70:73], v[178:181], v[214:217], v[70:73]
	v_mfma_f32_16x16x32_bf16 v[74:77], v[170:173], v[214:217], 0
	v_mfma_f32_16x16x32_bf16 v[74:77], v[166:169], v[210:213], v[74:77]
	s_setprio 0
	s_barrier
	s_add_i32 s33, s33, s40
	s_mov_b32 m0, s33
	ds_read_b128 v[182:185], v160 offset:16384
	ds_read_b128 v[186:189], v160 offset:17408
	ds_read_b128 v[190:193], v160 offset:18432
	ds_read_b128 v[194:197], v160 offset:19456
	ds_read_b128 v[198:201], v160 offset:20480
	ds_read_b128 v[206:209], v160 offset:21504
	ds_read_b128 v[210:213], v160 offset:22528
	ds_read_b128 v[214:217], v160 offset:23552
	global_load_lds_dwordx4 v0, s[28:29]
	s_add_i32 m0, s33, 0x2000
	s_add_u32 s100, s30, 0x80
	s_addc_u32 s101, s31, 0
	s_add_u32 s58, s28, 0x80000
	s_addc_u32 s59, s29, 0
	s_add_i32 s33, s57, s40
	global_load_lds_dwordx4 v14, s[28:29]
	s_mov_b32 m0, s33
	s_nop 0
	global_load_lds_dwordx4 v0, s[58:59]
	s_add_i32 m0, s33, 0x2000
	s_nop 0
	global_load_lds_dwordx4 v14, s[58:59]
	s_mov_b32 m0, s42
	s_nop 0
	global_load_lds_dwordx4 v136, s[30:31]
	s_mov_b32 m0, s43
	s_nop 0
	global_load_lds_dwordx4 v134, s[30:31]
	s_waitcnt vmcnt(8)
	s_waitcnt lgkmcnt(0)
	s_barrier
; #define PG8_STAGE(bufoff, gbase, voff) do { _Pragma("unroll") for (int _i = 0; _i < 2; ++_i) \
;         __builtin_amdgcn_global_load_lds((const unsigned*)((const char*)(gbase) + (voff)[_i]), (PG8_LAS unsigned*)(lds + (bufoff) + ldsw + _i * 8192), 16, 0, 0); } while (0)
; #define PG8_LDA(dst, b, h) do { _Pragma("unroll") for (int m = 0; m < 4; ++m) _Pragma("unroll") for (int k = 0; k < 2; ++k) dst[m][k] = *(const PG8_LAS bf16x8*)(lds + PG8_SA(b, h) + aoff + m * 2048 + k * 1024); } while (0)
; #define PG8_LDB(dst, b, h) do { _Pragma("unroll") for (int n = 0; n < 2; ++n) _Pragma("unroll") for (int k = 0; k < 2; ++k) dst[n][k] = *(const PG8_LAS bf16x8*)(lds + PG8_SB(b, h) + boff + n * 2048 + k * 1024); } while (0)
; #define PG8_MMA(ai, bj, At, Bt) do { __builtin_amdgcn_s_setprio(1); _Pragma("unroll") for (int m = 0; m < 4; ++m) _Pragma("unroll") for (int n = 0; n < 2; ++n) _Pragma("unroll") for (int k = 0; k < 2; ++k) \
;         acc[ai][bj][m][n] = __builtin_amdgcn_mfma_f32_16x16x32_bf16(Bt[n][k], At[m][k], acc[ai][bj][m][n], 0, 0, 0); __builtin_amdgcn_s_setprio(0); } while (0)
; #define PG8_WAIT_V(n) asm volatile("s_waitcnt vmcnt(" #n ")" ::: "memory")
; #define PG8_WAIT_L(n) asm volatile("s_waitcnt lgkmcnt(" #n ")" ::: "memory")
; #define PG8_BAR __builtin_amdgcn_s_barrier()
; #define PG8_SCHED __builtin_amdgcn_sched_barrier(0)
; template <class Epi, class Sched, bool ALIGN_EPI = false, bool SP2 = false>
; __device__ __forceinline__ void gemm_phase(PG8_LAS unsigned char* lds, const Gemm g, const Sched& S, const Epi& E) {
;     ...
;             PG8_WAIT_V(8); PG8_WAIT_L(0); PG8_BAR; PG8_MMA(1, 0, At, B0); PG8_MMA(1, 1, At, B1); PG8_BAR; PG8_SCHED;
;             PG8_LDB(B0, 1, 0); PG8_LDB(B1, 1, 1); PG8_SCHED; PG8_LDA(At, 1, 0); PG8_STAGE(PG8_SA(0, 1), a2 + hstep, voffA);
;             PG8_WAIT_V(8); PG8_WAIT_L(0); PG8_BAR; PG8_MMA(0, 0, At, B0); PG8_MMA(0, 1, At, B1); PG8_BAR; PG8_SCHED;
	s_setprio 1
	s_waitcnt lgkmcnt(0)
	v_mfma_f32_16x16x32_bf16 v[66:69], v[142:145], v[182:185], 0
	v_mfma_f32_16x16x32_bf16 v[66:69], v[146:149], v[186:189], v[66:69]
	v_mfma_f32_16x16x32_bf16 v[62:65], v[162:165], v[186:189], 0
	v_mfma_f32_16x16x32_bf16 v[62:65], v[150:153], v[182:185], v[62:65]
	v_mfma_f32_16x16x32_bf16 v[46:49], v[150:153], v[190:193], 0
	v_mfma_f32_16x16x32_bf16 v[46:49], v[162:165], v[194:197], v[46:49]
	v_mfma_f32_16x16x32_bf16 v[50:53], v[146:149], v[194:197], 0
	v_mfma_f32_16x16x32_bf16 v[50:53], v[142:145], v[190:193], v[50:53]
	v_mfma_f32_16x16x32_bf16 v[34:37], v[142:145], v[198:201], 0
	v_mfma_f32_16x16x32_bf16 v[34:37], v[146:149], v[206:209], v[34:37]
	v_mfma_f32_16x16x32_bf16 v[30:33], v[162:165], v[206:209], 0
	v_mfma_f32_16x16x32_bf16 v[30:33], v[150:153], v[198:201], v[30:33]
	v_mfma_f32_16x16x32_bf16 v[10:13], v[150:153], v[210:213], 0
	v_mfma_f32_16x16x32_bf16 v[10:13], v[162:165], v[214:217], v[10:13]
	v_mfma_f32_16x16x32_bf16 v[18:21], v[146:149], v[214:217], 0
	v_mfma_f32_16x16x32_bf16 v[18:21], v[142:145], v[210:213], v[18:21]
	s_setprio 0
	s_setprio 1
	v_mfma_f32_16x16x32_bf16 v[58:61], v[166:169], v[182:185], 0
	v_mfma_f32_16x16x32_bf16 v[58:61], v[170:173], v[186:189], v[58:61]
	v_mfma_f32_16x16x32_bf16 v[54:57], v[178:181], v[186:189], 0
	v_mfma_f32_16x16x32_bf16 v[54:57], v[174:177], v[182:185], v[54:57]
	v_mfma_f32_16x16x32_bf16 v[38:41], v[174:177], v[190:193], 0
	v_mfma_f32_16x16x32_bf16 v[38:41], v[178:181], v[194:197], v[38:41]
	v_mfma_f32_16x16x32_bf16 v[42:45], v[170:173], v[194:197], 0
	v_mfma_f32_16x16x32_bf16 v[42:45], v[166:169], v[190:193], v[42:45]
	v_mfma_f32_16x16x32_bf16 v[26:29], v[166:169], v[198:201], 0
	v_mfma_f32_16x16x32_bf16 v[26:29], v[170:173], v[206:209], v[26:29]
	v_mfma_f32_16x16x32_bf16 v[22:25], v[178:181], v[206:209], 0
	v_mfma_f32_16x16x32_bf16 v[22:25], v[174:177], v[198:201], v[22:25]
	v_mfma_f32_16x16x32_bf16 v[2:5], v[174:177], v[210:213], 0
	v_mfma_f32_16x16x32_bf16 v[2:5], v[178:181], v[214:217], v[2:5]
	v_mfma_f32_16x16x32_bf16 v[6:9], v[170:173], v[214:217], 0
	v_mfma_f32_16x16x32_bf16 v[6:9], v[166:169], v[210:213], v[6:9]
	s_setprio 0
	s_barrier
	s_add_i32 s33, 0, 0x18000
	s_add_i32 s57, 0, 0x1c000
	ds_read_b128 v[142:145], v226 offset:32768
	ds_read_b128 v[146:149], v226 offset:33792
	ds_read_b128 v[150:153], v226 offset:34816
	ds_read_b128 v[162:165], v226 offset:35840
	ds_read_b128 v[166:169], v226 offset:49152
	ds_read_b128 v[170:173], v226 offset:50176
	ds_read_b128 v[174:177], v226 offset:51200
	ds_read_b128 v[178:181], v226 offset:52224
	s_add_u32 s30, s30, 0x80000
	s_addc_u32 s31, s31, 0
	s_mov_b32 m0, s44
	ds_read_b128 v[182:185], v160 offset:32768
	ds_read_b128 v[186:189], v160 offset:33792
	ds_read_b128 v[190:193], v160 offset:34816
	ds_read_b128 v[194:197], v160 offset:35840
	ds_read_b128 v[198:201], v160 offset:36864
	ds_read_b128 v[206:209], v160 offset:37888
	ds_read_b128 v[210:213], v160 offset:38912
	ds_read_b128 v[214:217], v160 offset:39936
	global_load_lds_dwordx4 v136, s[30:31]
	s_mov_b32 m0, s45
	s_nop 0
	global_load_lds_dwordx4 v134, s[30:31]
	s_waitcnt vmcnt(8)
	s_waitcnt lgkmcnt(0)
	s_barrier
	s_setprio 1
	s_waitcnt lgkmcnt(0)
	v_mfma_f32_16x16x32_bf16 v[130:133], v[142:145], v[182:185], v[130:133]
	v_mfma_f32_16x16x32_bf16 v[130:133], v[146:149], v[186:189], v[130:133]
	v_mfma_f32_16x16x32_bf16 v[126:129], v[162:165], v[186:189], v[126:129]
	v_mfma_f32_16x16x32_bf16 v[126:129], v[150:153], v[182:185], v[126:129]
	v_mfma_f32_16x16x32_bf16 v[110:113], v[150:153], v[190:193], v[110:113]
	v_mfma_f32_16x16x32_bf16 v[110:113], v[162:165], v[194:197], v[110:113]
	v_mfma_f32_16x16x32_bf16 v[114:117], v[146:149], v[194:197], v[114:117]
	v_mfma_f32_16x16x32_bf16 v[114:117], v[142:145], v[190:193], v[114:117]
	v_mfma_f32_16x16x32_bf16 v[98:101], v[142:145], v[198:201], v[98:101]
	v_mfma_f32_16x16x32_bf16 v[98:101], v[146:149], v[206:209], v[98:101]
	v_mfma_f32_16x16x32_bf16 v[94:97], v[162:165], v[206:209], v[94:97]
	v_mfma_f32_16x16x32_bf16 v[94:97], v[150:153], v[198:201], v[94:97]
	v_mfma_f32_16x16x32_bf16 v[78:81], v[150:153], v[210:213], v[78:81]
	v_mfma_f32_16x16x32_bf16 v[78:81], v[162:165], v[214:217], v[78:81]
	v_mfma_f32_16x16x32_bf16 v[82:85], v[146:149], v[214:217], v[82:85]
	v_mfma_f32_16x16x32_bf16 v[82:85], v[142:145], v[210:213], v[82:85]
	s_setprio 0
	s_setprio 1
	v_mfma_f32_16x16x32_bf16 v[122:125], v[166:169], v[182:185], v[122:125]
	v_mfma_f32_16x16x32_bf16 v[122:125], v[170:173], v[186:189], v[122:125]
	v_mfma_f32_16x16x32_bf16 v[118:121], v[178:181], v[186:189], v[118:121]
	v_mfma_f32_16x16x32_bf16 v[118:121], v[174:177], v[182:185], v[118:121]
	v_mfma_f32_16x16x32_bf16 v[102:105], v[174:177], v[190:193], v[102:105]
	v_mfma_f32_16x16x32_bf16 v[102:105], v[178:181], v[194:197], v[102:105]
	v_mfma_f32_16x16x32_bf16 v[106:109], v[170:173], v[194:197], v[106:109]
	v_mfma_f32_16x16x32_bf16 v[106:109], v[166:169], v[190:193], v[106:109]
	v_mfma_f32_16x16x32_bf16 v[90:93], v[166:169], v[198:201], v[90:93]
	v_mfma_f32_16x16x32_bf16 v[90:93], v[170:173], v[206:209], v[90:93]
	v_mfma_f32_16x16x32_bf16 v[86:89], v[178:181], v[206:209], v[86:89]
	v_mfma_f32_16x16x32_bf16 v[86:89], v[174:177], v[198:201], v[86:89]
	v_mfma_f32_16x16x32_bf16 v[70:73], v[174:177], v[210:213], v[70:73]
	v_mfma_f32_16x16x32_bf16 v[70:73], v[178:181], v[214:217], v[70:73]
	v_mfma_f32_16x16x32_bf16 v[74:77], v[170:173], v[214:217], v[74:77]
	v_mfma_f32_16x16x32_bf16 v[74:77], v[166:169], v[210:213], v[74:77]
	s_setprio 0
	s_barrier
; #define PG8_STAGE(bufoff, gbase, voff) do { _Pragma("unroll") for (int _i = 0; _i < 2; ++_i) \
;         __builtin_amdgcn_global_load_lds((const unsigned*)((const char*)(gbase) + (voff)[_i]), (PG8_LAS unsigned*)(lds + (bufoff) + ldsw + _i * 8192), 16, 0, 0); } while (0)
; #define PG8_LDA(dst, b, h) do { _Pragma("unroll") for (int m = 0; m < 4; ++m) _Pragma("unroll") for (int k = 0; k < 2; ++k) dst[m][k] = *(const PG8_LAS bf16x8*)(lds + PG8_SA(b, h) + aoff + m * 2048 + k * 1024); } while (0)
; #define PG8_LDB(dst, b, h) do { _Pragma("unroll") for (int n = 0; n < 2; ++n) _Pragma("unroll") for (int k = 0; k < 2; ++k) dst[n][k] = *(const PG8_LAS bf16x8*)(lds + PG8_SB(b, h) + boff + n * 2048 + k * 1024); } while (0)
; #define PG8_MMA(ai, bj, At, Bt) do { __builtin_amdgcn_s_setprio(1); _Pragma("unroll") for (int m = 0; m < 4; ++m) _Pragma("unroll") for (int n = 0; n < 2; ++n) _Pragma("unroll") for (int k = 0; k < 2; ++k) \
;         acc[ai][bj][m][n] = __builtin_amdgcn_mfma_f32_16x16x32_bf16(Bt[n][k], At[m][k], acc[ai][bj][m][n], 0, 0, 0); __builtin_amdgcn_s_setprio(0); } while (0)
; #define PG8_WAIT_V(n) asm volatile("s_waitcnt vmcnt(" #n ")" ::: "memory")
; template <class Epi, class Sched, bool ALIGN_EPI = false, bool SP2 = false>
; __device__ __forceinline__ void gemm_phase(PG8_LAS unsigned char* lds, const Gemm g, const Sched& S, const Epi& E) {
;     ...
;             const bool last = (t == nt - 2);
;             const char* a1 = cA + (size_t)(t + 1) * kstep;
;             const char* a2 = last ? nA : cA + (size_t)(t + 2) * kstep; const char* b2 = last ? nB : cB + (size_t)(t + 2) * kstep;
;             const char* a3 = a2 + kstep; const char* b3 = b2 + kstep;
;             if (last && has_next) S.a_ready(nxt);
;             if constexpr (Epi::MID) { if (t == nt / 2) E.mid(acc, cur, wr, wc, fr, fq); }
;             if constexpr (SP2) {
;             PG8_LDB(B0, 0, 0); PG8_LDB(B1, 0, 1); PG8_SCHED; PG8_LDA(At, 0, 0); PG8_STAGE(PG8_SA(1, 1), a1 + hstep, voffA);
;             PG8_WAIT_V(8); PG8_WAIT_L(0); PG8_BAR; PG8_MMA(0, 0, At, B0); PG8_MMA(0, 1, At, B1); PG8_BAR; PG8_SCHED;
;     ...
;             PG8_LDA(At, 1, 1); PG8_STAGE(PG8_SB(1, 0), b3, voffB); PG8_STAGE(PG8_SB(1, 1), b3 + hstep, voffB); PG8_STAGE(PG8_SA(1, 0), a3, voffA);
;             PG8_WAIT_V(8); PG8_WAIT_L(0); PG8_BAR; PG8_MMA(1, 0, At, B0); PG8_MMA(1, 1, At, B1); PG8_BAR; PG8_SCHED;
	s_add_i32 s30, s33, s40
	s_add_i32 m0, s30, 0xffffff80
	ds_read_b128 v[182:185], v160 offset:49152
	ds_read_b128 v[186:189], v160 offset:50176
	ds_read_b128 v[190:193], v160 offset:51200
	ds_read_b128 v[194:197], v160 offset:52224
	ds_read_b128 v[198:201], v160 offset:53248
	ds_read_b128 v[206:209], v160 offset:54272
	ds_read_b128 v[210:213], v160 offset:55296
	ds_read_b128 v[214:217], v160 offset:56320
	global_load_lds_dwordx4 v0, s[28:29] offset:128
	s_add_i32 m0, s30, 0x1f80
	s_add_i32 s30, s57, s40
	global_load_lds_dwordx4 v14, s[28:29] offset:128
	s_add_u32 s28, s28, 0x80080
	s_addc_u32 s29, s29, 0
	s_mov_b32 m0, s30
	s_nop 0
	global_load_lds_dwordx4 v0, s[28:29]
	s_add_i32 m0, s30, 0x2000
	s_nop 0
	global_load_lds_dwordx4 v14, s[28:29]
	s_mov_b32 m0, s47
	s_nop 0
	global_load_lds_dwordx4 v136, s[100:101]
	s_mov_b32 m0, s48
	s_nop 0
	global_load_lds_dwordx4 v134, s[100:101]
	s_waitcnt vmcnt(8)
	s_waitcnt lgkmcnt(0)
	s_barrier
	s_setprio 1
	s_waitcnt lgkmcnt(0)
	v_mfma_f32_16x16x32_bf16 v[66:69], v[142:145], v[182:185], v[66:69]
	v_mfma_f32_16x16x32_bf16 v[66:69], v[146:149], v[186:189], v[66:69]
	v_mfma_f32_16x16x32_bf16 v[62:65], v[162:165], v[186:189], v[62:65]
	v_mfma_f32_16x16x32_bf16 v[62:65], v[150:153], v[182:185], v[62:65]
	v_mfma_f32_16x16x32_bf16 v[46:49], v[150:153], v[190:193], v[46:49]
	v_mfma_f32_16x16x32_bf16 v[46:49], v[162:165], v[194:197], v[46:49]
	v_mfma_f32_16x16x32_bf16 v[50:53], v[146:149], v[194:197], v[50:53]
	v_mfma_f32_16x16x32_bf16 v[50:53], v[142:145], v[190:193], v[50:53]
	v_mfma_f32_16x16x32_bf16 v[34:37], v[142:145], v[198:201], v[34:37]
	v_mfma_f32_16x16x32_bf16 v[34:37], v[146:149], v[206:209], v[34:37]
	v_mfma_f32_16x16x32_bf16 v[30:33], v[162:165], v[206:209], v[30:33]
	v_mfma_f32_16x16x32_bf16 v[30:33], v[150:153], v[198:201], v[30:33]
	v_mfma_f32_16x16x32_bf16 v[10:13], v[150:153], v[210:213], v[10:13]
	v_mfma_f32_16x16x32_bf16 v[10:13], v[162:165], v[214:217], v[10:13]
	v_mfma_f32_16x16x32_bf16 v[18:21], v[146:149], v[214:217], v[18:21]
	v_mfma_f32_16x16x32_bf16 v[18:21], v[142:145], v[210:213], v[18:21]
	s_setprio 0
	s_setprio 1
	v_mfma_f32_16x16x32_bf16 v[58:61], v[166:169], v[182:185], v[58:61]
	v_mfma_f32_16x16x32_bf16 v[58:61], v[170:173], v[186:189], v[58:61]
	v_mfma_f32_16x16x32_bf16 v[54:57], v[178:181], v[186:189], v[54:57]
	v_mfma_f32_16x16x32_bf16 v[54:57], v[174:177], v[182:185], v[54:57]
	v_mfma_f32_16x16x32_bf16 v[38:41], v[174:177], v[190:193], v[38:41]
	v_mfma_f32_16x16x32_bf16 v[38:41], v[178:181], v[194:197], v[38:41]
	v_mfma_f32_16x16x32_bf16 v[42:45], v[170:173], v[194:197], v[42:45]
	v_mfma_f32_16x16x32_bf16 v[42:45], v[166:169], v[190:193], v[42:45]
	v_mfma_f32_16x16x32_bf16 v[26:29], v[166:169], v[198:201], v[26:29]
	v_mfma_f32_16x16x32_bf16 v[26:29], v[170:173], v[206:209], v[26:29]
	v_mfma_f32_16x16x32_bf16 v[22:25], v[178:181], v[206:209], v[22:25]
	v_mfma_f32_16x16x32_bf16 v[22:25], v[174:177], v[198:201], v[22:25]
	v_mfma_f32_16x16x32_bf16 v[2:5], v[174:177], v[210:213], v[2:5]
	v_mfma_f32_16x16x32_bf16 v[2:5], v[178:181], v[214:217], v[2:5]
	v_mfma_f32_16x16x32_bf16 v[6:9], v[170:173], v[214:217], v[6:9]
	v_mfma_f32_16x16x32_bf16 v[6:9], v[166:169], v[210:213], v[6:9]
	s_setprio 0
	s_barrier
	s_add_i32 s56, s56, 2
	s_add_u32 s54, s54, 0x100
	s_addc_u32 s55, s55, 0
	s_add_u32 s26, s26, 0x100
	s_addc_u32 s27, s27, 0
	s_cmp_gt_u32 s56, 29
.LBB0_1223:
	s_add_u32 s28, s26, 0xfff80080
	s_addc_u32 s29, s27, -1
	s_add_i32 s33, 0, 0x10000
	s_cmp_eq_u32 s56, 28
	s_cselect_b32 s31, s5, s29
	s_cselect_b32 s30, s11, s28
	s_cselect_b32 s29, s19, s55
	s_cselect_b32 s28, s21, s54
	s_add_i32 s57, 0, 0x14000
	ds_read_b128 v[142:145], v226
	ds_read_b128 v[146:149], v226 offset:1024
	ds_read_b128 v[150:153], v226 offset:2048
	ds_read_b128 v[162:165], v226 offset:3072
	ds_read_b128 v[166:169], v226 offset:16384
	ds_read_b128 v[170:173], v226 offset:17408
	ds_read_b128 v[174:177], v226 offset:18432
	ds_read_b128 v[178:181], v226 offset:19456
	s_add_i32 m0, s42, 0xc000
	ds_read_b128 v[182:185], v160
	ds_read_b128 v[186:189], v160 offset:1024
	ds_read_b128 v[190:193], v160 offset:2048
	ds_read_b128 v[194:197], v160 offset:3072
	ds_read_b128 v[198:201], v160 offset:4096
	ds_read_b128 v[206:209], v160 offset:5120
	ds_read_b128 v[210:213], v160 offset:6144
	ds_read_b128 v[214:217], v160 offset:7168
	global_load_lds_dwordx4 v140, s[26:27]
	s_add_i32 m0, s42, 0xe000
	s_nop 0
	global_load_lds_dwordx4 v138, s[26:27]
	s_waitcnt vmcnt(8)
	s_waitcnt lgkmcnt(0)
	s_barrier
; #define PG8_STAGE(bufoff, gbase, voff) do { _Pragma("unroll") for (int _i = 0; _i < 2; ++_i) \
;         __builtin_amdgcn_global_load_lds((const unsigned*)((const char*)(gbase) + (voff)[_i]), (PG8_LAS unsigned*)(lds + (bufoff) + ldsw + _i * 8192), 16, 0, 0); } while (0)
; #define PG8_LDA(dst, b, h) do { _Pragma("unroll") for (int m = 0; m < 4; ++m) _Pragma("unroll") for (int k = 0; k < 2; ++k) dst[m][k] = *(const PG8_LAS bf16x8*)(lds + PG8_SA(b, h) + aoff + m * 2048 + k * 1024); } while (0)
; #define PG8_MMA(ai, bj, At, Bt) do { __builtin_amdgcn_s_setprio(1); _Pragma("unroll") for (int m = 0; m < 4; ++m) _Pragma("unroll") for (int n = 0; n < 2; ++n) _Pragma("unroll") for (int k = 0; k < 2; ++k) \
;         acc[ai][bj][m][n] = __builtin_amdgcn_mfma_f32_16x16x32_bf16(Bt[n][k], At[m][k], acc[ai][bj][m][n], 0, 0, 0); __builtin_amdgcn_s_setprio(0); } while (0)
; #define PG8_WAIT_V(n) asm volatile("s_waitcnt vmcnt(" #n ")" ::: "memory")
; #define PG8_WAIT_L(n) asm volatile("s_waitcnt lgkmcnt(" #n ")" ::: "memory")
; #define PG8_BAR __builtin_amdgcn_s_barrier()
; #define PG8_SCHED __builtin_amdgcn_sched_barrier(0)
; template <class Epi, class Sched, bool ALIGN_EPI = false, bool SP2 = false>
; __device__ __forceinline__ void gemm_phase(PG8_LAS unsigned char* lds, const Gemm g, const Sched& S, const Epi& E) {
;     ...
;             PG8_WAIT_V(8); PG8_WAIT_L(0); PG8_BAR; PG8_MMA(0, 0, At, B0); PG8_MMA(0, 1, At, B1); PG8_BAR; PG8_SCHED;
;             PG8_LDA(At, 0, 1); PG8_STAGE(PG8_SB(0, 0), b2, voffB); PG8_STAGE(PG8_SB(0, 1), b2 + hstep, voffB); PG8_STAGE(PG8_SA(0, 0), a2, voffA);
;             PG8_WAIT_V(8); PG8_WAIT_L(0); PG8_BAR; PG8_MMA(1, 0, At, B0); PG8_MMA(1, 1, At, B1); PG8_BAR; PG8_SCHED;
	s_setprio 1
	s_waitcnt lgkmcnt(0)
	v_mfma_f32_16x16x32_bf16 v[130:133], v[142:145], v[182:185], v[130:133]
	v_mfma_f32_16x16x32_bf16 v[130:133], v[146:149], v[186:189], v[130:133]
	v_mfma_f32_16x16x32_bf16 v[126:129], v[162:165], v[186:189], v[126:129]
	v_mfma_f32_16x16x32_bf16 v[126:129], v[150:153], v[182:185], v[126:129]
	v_mfma_f32_16x16x32_bf16 v[110:113], v[150:153], v[190:193], v[110:113]
	v_mfma_f32_16x16x32_bf16 v[110:113], v[162:165], v[194:197], v[110:113]
	v_mfma_f32_16x16x32_bf16 v[114:117], v[146:149], v[194:197], v[114:117]
	v_mfma_f32_16x16x32_bf16 v[114:117], v[142:145], v[190:193], v[114:117]
	v_mfma_f32_16x16x32_bf16 v[98:101], v[142:145], v[198:201], v[98:101]
	v_mfma_f32_16x16x32_bf16 v[98:101], v[146:149], v[206:209], v[98:101]
	v_mfma_f32_16x16x32_bf16 v[94:97], v[162:165], v[206:209], v[94:97]
	v_mfma_f32_16x16x32_bf16 v[94:97], v[150:153], v[198:201], v[94:97]
	v_mfma_f32_16x16x32_bf16 v[78:81], v[150:153], v[210:213], v[78:81]
	v_mfma_f32_16x16x32_bf16 v[78:81], v[162:165], v[214:217], v[78:81]
	v_mfma_f32_16x16x32_bf16 v[82:85], v[146:149], v[214:217], v[82:85]
	v_mfma_f32_16x16x32_bf16 v[82:85], v[142:145], v[210:213], v[82:85]
	s_setprio 0
	s_setprio 1
	v_mfma_f32_16x16x32_bf16 v[122:125], v[166:169], v[182:185], v[122:125]
	v_mfma_f32_16x16x32_bf16 v[122:125], v[170:173], v[186:189], v[122:125]
	v_mfma_f32_16x16x32_bf16 v[118:121], v[178:181], v[186:189], v[118:121]
	v_mfma_f32_16x16x32_bf16 v[118:121], v[174:177], v[182:185], v[118:121]
	v_mfma_f32_16x16x32_bf16 v[102:105], v[174:177], v[190:193], v[102:105]
	v_mfma_f32_16x16x32_bf16 v[102:105], v[178:181], v[194:197], v[102:105]
	v_mfma_f32_16x16x32_bf16 v[106:109], v[170:173], v[194:197], v[106:109]
	v_mfma_f32_16x16x32_bf16 v[106:109], v[166:169], v[190:193], v[106:109]
	v_mfma_f32_16x16x32_bf16 v[90:93], v[166:169], v[198:201], v[90:93]
	v_mfma_f32_16x16x32_bf16 v[90:93], v[170:173], v[206:209], v[90:93]
	v_mfma_f32_16x16x32_bf16 v[86:89], v[178:181], v[206:209], v[86:89]
	v_mfma_f32_16x16x32_bf16 v[86:89], v[174:177], v[198:201], v[86:89]
	v_mfma_f32_16x16x32_bf16 v[70:73], v[174:177], v[210:213], v[70:73]
	v_mfma_f32_16x16x32_bf16 v[70:73], v[178:181], v[214:217], v[70:73]
	v_mfma_f32_16x16x32_bf16 v[74:77], v[170:173], v[214:217], v[74:77]
	v_mfma_f32_16x16x32_bf16 v[74:77], v[166:169], v[210:213], v[74:77]
	s_setprio 0
	s_barrier
	s_add_i32 s33, s33, s40
	s_mov_b32 m0, s33
	ds_read_b128 v[182:185], v160 offset:16384
	ds_read_b128 v[186:189], v160 offset:17408
	ds_read_b128 v[190:193], v160 offset:18432
	ds_read_b128 v[194:197], v160 offset:19456
	ds_read_b128 v[198:201], v160 offset:20480
	ds_read_b128 v[206:209], v160 offset:21504
	ds_read_b128 v[210:213], v160 offset:22528
	ds_read_b128 v[214:217], v160 offset:23552
	global_load_lds_dwordx4 v0, s[28:29]
	s_add_i32 m0, s33, 0x2000
	s_add_u32 s100, s30, 0x80
	s_addc_u32 s101, s31, 0
	s_add_u32 s58, s28, 0x80000
	s_addc_u32 s59, s29, 0
	s_add_i32 s33, s57, s40
	global_load_lds_dwordx4 v14, s[28:29]
	s_mov_b32 m0, s33
	s_nop 0
	global_load_lds_dwordx4 v0, s[58:59]
	s_add_i32 m0, s33, 0x2000
	s_nop 0
	global_load_lds_dwordx4 v14, s[58:59]
	s_mov_b32 m0, s42
	s_nop 0
	global_load_lds_dwordx4 v136, s[30:31]
	s_mov_b32 m0, s43
	s_nop 0
	global_load_lds_dwordx4 v134, s[30:31]
	s_waitcnt vmcnt(8)
	s_waitcnt lgkmcnt(0)
	s_barrier
	s_setprio 1
	s_waitcnt lgkmcnt(0)
	v_mfma_f32_16x16x32_bf16 v[66:69], v[142:145], v[182:185], v[66:69]
	v_mfma_f32_16x16x32_bf16 v[66:69], v[146:149], v[186:189], v[66:69]
	v_mfma_f32_16x16x32_bf16 v[62:65], v[162:165], v[186:189], v[62:65]
	v_mfma_f32_16x16x32_bf16 v[62:65], v[150:153], v[182:185], v[62:65]
	v_mfma_f32_16x16x32_bf16 v[46:49], v[150:153], v[190:193], v[46:49]
	v_mfma_f32_16x16x32_bf16 v[46:49], v[162:165], v[194:197], v[46:49]
	v_mfma_f32_16x16x32_bf16 v[50:53], v[146:149], v[194:197], v[50:53]
	v_mfma_f32_16x16x32_bf16 v[50:53], v[142:145], v[190:193], v[50:53]
	v_mfma_f32_16x16x32_bf16 v[34:37], v[142:145], v[198:201], v[34:37]
	v_mfma_f32_16x16x32_bf16 v[34:37], v[146:149], v[206:209], v[34:37]
	v_mfma_f32_16x16x32_bf16 v[30:33], v[162:165], v[206:209], v[30:33]
	v_mfma_f32_16x16x32_bf16 v[30:33], v[150:153], v[198:201], v[30:33]
	v_mfma_f32_16x16x32_bf16 v[10:13], v[150:153], v[210:213], v[10:13]
	v_mfma_f32_16x16x32_bf16 v[10:13], v[162:165], v[214:217], v[10:13]
	v_mfma_f32_16x16x32_bf16 v[18:21], v[146:149], v[214:217], v[18:21]
	v_mfma_f32_16x16x32_bf16 v[18:21], v[142:145], v[210:213], v[18:21]
	s_setprio 0
	s_setprio 1
	v_mfma_f32_16x16x32_bf16 v[58:61], v[166:169], v[182:185], v[58:61]
	v_mfma_f32_16x16x32_bf16 v[58:61], v[170:173], v[186:189], v[58:61]
	v_mfma_f32_16x16x32_bf16 v[54:57], v[178:181], v[186:189], v[54:57]
	v_mfma_f32_16x16x32_bf16 v[54:57], v[174:177], v[182:185], v[54:57]
	v_mfma_f32_16x16x32_bf16 v[38:41], v[174:177], v[190:193], v[38:41]
	v_mfma_f32_16x16x32_bf16 v[38:41], v[178:181], v[194:197], v[38:41]
	v_mfma_f32_16x16x32_bf16 v[42:45], v[170:173], v[194:197], v[42:45]
	v_mfma_f32_16x16x32_bf16 v[42:45], v[166:169], v[190:193], v[42:45]
	v_mfma_f32_16x16x32_bf16 v[26:29], v[166:169], v[198:201], v[26:29]
	v_mfma_f32_16x16x32_bf16 v[26:29], v[170:173], v[206:209], v[26:29]
	v_mfma_f32_16x16x32_bf16 v[22:25], v[178:181], v[206:209], v[22:25]
	v_mfma_f32_16x16x32_bf16 v[22:25], v[174:177], v[198:201], v[22:25]
	v_mfma_f32_16x16x32_bf16 v[2:5], v[174:177], v[210:213], v[2:5]
	v_mfma_f32_16x16x32_bf16 v[2:5], v[178:181], v[214:217], v[2:5]
	v_mfma_f32_16x16x32_bf16 v[6:9], v[170:173], v[214:217], v[6:9]
	v_mfma_f32_16x16x32_bf16 v[6:9], v[166:169], v[210:213], v[6:9]
	s_setprio 0
	s_barrier
; #define PG8_STAGE(bufoff, gbase, voff) do { _Pragma("unroll") for (int _i = 0; _i < 2; ++_i) \
;         __builtin_amdgcn_global_load_lds((const unsigned*)((const char*)(gbase) + (voff)[_i]), (PG8_LAS unsigned*)(lds + (bufoff) + ldsw + _i * 8192), 16, 0, 0); } while (0)
; #define PG8_LDA(dst, b, h) do { _Pragma("unroll") for (int m = 0; m < 4; ++m) _Pragma("unroll") for (int k = 0; k < 2; ++k) dst[m][k] = *(const PG8_LAS bf16x8*)(lds + PG8_SA(b, h) + aoff + m * 2048 + k * 1024); } while (0)
; #define PG8_LDB(dst, b, h) do { _Pragma("unroll") for (int n = 0; n < 2; ++n) _Pragma("unroll") for (int k = 0; k < 2; ++k) dst[n][k] = *(const PG8_LAS bf16x8*)(lds + PG8_SB(b, h) + boff + n * 2048 + k * 1024); } while (0)
; #define PG8_MMA(ai, bj, At, Bt) do { __builtin_amdgcn_s_setprio(1); _Pragma("unroll") for (int m = 0; m < 4; ++m) _Pragma("unroll") for (int n = 0; n < 2; ++n) _Pragma("unroll") for (int k = 0; k < 2; ++k) \
;         acc[ai][bj][m][n] = __builtin_amdgcn_mfma_f32_16x16x32_bf16(Bt[n][k], At[m][k], acc[ai][bj][m][n], 0, 0, 0); __builtin_amdgcn_s_setprio(0); } while (0)
; #define PG8_WAIT_V(n) asm volatile("s_waitcnt vmcnt(" #n ")" ::: "memory")
; #define PG8_WAIT_L(n) asm volatile("s_waitcnt lgkmcnt(" #n ")" ::: "memory")
; #define PG8_BAR __builtin_amdgcn_s_barrier()
; #define PG8_SCHED __builtin_amdgcn_sched_barrier(0)
; template <class Epi, class Sched, bool ALIGN_EPI = false, bool SP2 = false>
; __device__ __forceinline__ void gemm_phase(PG8_LAS unsigned char* lds, const Gemm g, const Sched& S, const Epi& E) {
;     ...
;             PG8_LDB(B0, 1, 0); PG8_LDB(B1, 1, 1); PG8_SCHED; PG8_LDA(At, 1, 0); PG8_STAGE(PG8_SA(0, 1), a2 + hstep, voffA);
;             PG8_WAIT_V(8); PG8_WAIT_L(0); PG8_BAR; PG8_MMA(0, 0, At, B0); PG8_MMA(0, 1, At, B1); PG8_BAR; PG8_SCHED;
;             PG8_LDA(At, 1, 1); PG8_STAGE(PG8_SB(1, 0), b3, voffB); PG8_STAGE(PG8_SB(1, 1), b3 + hstep, voffB); PG8_STAGE(PG8_SA(1, 0), a3, voffA);
;             PG8_WAIT_V(8); PG8_WAIT_L(0); PG8_BAR; PG8_MMA(1, 0, At, B0); PG8_MMA(1, 1, At, B1); PG8_BAR; PG8_SCHED;
;     ...
;         if constexpr (ALIGN_EPI) { if (wr == 0) PG8_BAR; }
	s_add_i32 s33, 0, 0x18000
	s_add_i32 s57, 0, 0x1c000
	ds_read_b128 v[142:145], v226 offset:32768
	ds_read_b128 v[146:149], v226 offset:33792
	ds_read_b128 v[150:153], v226 offset:34816
	ds_read_b128 v[162:165], v226 offset:35840
	ds_read_b128 v[166:169], v226 offset:49152
	ds_read_b128 v[170:173], v226 offset:50176
	ds_read_b128 v[174:177], v226 offset:51200
	ds_read_b128 v[178:181], v226 offset:52224
	s_add_u32 s30, s30, 0x80000
	s_addc_u32 s31, s31, 0
	s_mov_b32 m0, s44
	ds_read_b128 v[182:185], v160 offset:32768
	ds_read_b128 v[186:189], v160 offset:33792
	ds_read_b128 v[190:193], v160 offset:34816
	ds_read_b128 v[194:197], v160 offset:35840
	ds_read_b128 v[198:201], v160 offset:36864
	ds_read_b128 v[206:209], v160 offset:37888
	ds_read_b128 v[210:213], v160 offset:38912
	ds_read_b128 v[214:217], v160 offset:39936
	global_load_lds_dwordx4 v136, s[30:31]
	s_mov_b32 m0, s45
	s_nop 0
	global_load_lds_dwordx4 v134, s[30:31]
	s_waitcnt vmcnt(8)
	s_waitcnt lgkmcnt(0)
	s_barrier
	s_setprio 1
	s_waitcnt lgkmcnt(0)
	v_mfma_f32_16x16x32_bf16 v[130:133], v[142:145], v[182:185], v[130:133]
	v_mfma_f32_16x16x32_bf16 v[130:133], v[146:149], v[186:189], v[130:133]
	v_mfma_f32_16x16x32_bf16 v[126:129], v[162:165], v[186:189], v[126:129]
	v_mfma_f32_16x16x32_bf16 v[126:129], v[150:153], v[182:185], v[126:129]
	v_mfma_f32_16x16x32_bf16 v[110:113], v[150:153], v[190:193], v[110:113]
	v_mfma_f32_16x16x32_bf16 v[110:113], v[162:165], v[194:197], v[110:113]
	v_mfma_f32_16x16x32_bf16 v[114:117], v[146:149], v[194:197], v[114:117]
	v_mfma_f32_16x16x32_bf16 v[114:117], v[142:145], v[190:193], v[114:117]
	v_mfma_f32_16x16x32_bf16 v[98:101], v[142:145], v[198:201], v[98:101]
	v_mfma_f32_16x16x32_bf16 v[98:101], v[146:149], v[206:209], v[98:101]
	v_mfma_f32_16x16x32_bf16 v[94:97], v[162:165], v[206:209], v[94:97]
	v_mfma_f32_16x16x32_bf16 v[94:97], v[150:153], v[198:201], v[94:97]
	v_mfma_f32_16x16x32_bf16 v[78:81], v[150:153], v[210:213], v[78:81]
	v_mfma_f32_16x16x32_bf16 v[78:81], v[162:165], v[214:217], v[78:81]
	v_mfma_f32_16x16x32_bf16 v[82:85], v[146:149], v[214:217], v[82:85]
	v_mfma_f32_16x16x32_bf16 v[82:85], v[142:145], v[210:213], v[82:85]
	s_setprio 0
	s_setprio 1
	v_mfma_f32_16x16x32_bf16 v[122:125], v[166:169], v[182:185], v[122:125]
	v_mfma_f32_16x16x32_bf16 v[122:125], v[170:173], v[186:189], v[122:125]
	v_mfma_f32_16x16x32_bf16 v[118:121], v[178:181], v[186:189], v[118:121]
	v_mfma_f32_16x16x32_bf16 v[118:121], v[174:177], v[182:185], v[118:121]
	v_mfma_f32_16x16x32_bf16 v[102:105], v[174:177], v[190:193], v[102:105]
	v_mfma_f32_16x16x32_bf16 v[102:105], v[178:181], v[194:197], v[102:105]
	v_mfma_f32_16x16x32_bf16 v[106:109], v[170:173], v[194:197], v[106:109]
	v_mfma_f32_16x16x32_bf16 v[106:109], v[166:169], v[190:193], v[106:109]
	v_mfma_f32_16x16x32_bf16 v[90:93], v[166:169], v[198:201], v[90:93]
	v_mfma_f32_16x16x32_bf16 v[90:93], v[170:173], v[206:209], v[90:93]
	v_mfma_f32_16x16x32_bf16 v[86:89], v[178:181], v[206:209], v[86:89]
	v_mfma_f32_16x16x32_bf16 v[86:89], v[174:177], v[198:201], v[86:89]
	v_mfma_f32_16x16x32_bf16 v[70:73], v[174:177], v[210:213], v[70:73]
	v_mfma_f32_16x16x32_bf16 v[70:73], v[178:181], v[214:217], v[70:73]
	v_mfma_f32_16x16x32_bf16 v[74:77], v[170:173], v[214:217], v[74:77]
	v_mfma_f32_16x16x32_bf16 v[74:77], v[166:169], v[210:213], v[74:77]
	s_setprio 0
	s_barrier
	s_add_i32 s30, s33, s40
	s_add_i32 m0, s30, 0xffffff80
	ds_read_b128 v[182:185], v160 offset:49152
	ds_read_b128 v[186:189], v160 offset:50176
	ds_read_b128 v[190:193], v160 offset:51200
	ds_read_b128 v[194:197], v160 offset:52224
	ds_read_b128 v[198:201], v160 offset:53248
	ds_read_b128 v[206:209], v160 offset:54272
	ds_read_b128 v[210:213], v160 offset:55296
	ds_read_b128 v[214:217], v160 offset:56320
	global_load_lds_dwordx4 v0, s[28:29] offset:128
	s_add_i32 m0, s30, 0x1f80
	s_add_i32 s30, s57, s40
	global_load_lds_dwordx4 v14, s[28:29] offset:128
	s_add_u32 s28, s28, 0x80080
	s_addc_u32 s29, s29, 0
	s_mov_b32 m0, s30
	s_nop 0
	global_load_lds_dwordx4 v0, s[28:29]
	s_add_i32 m0, s30, 0x2000
	s_nop 0
	global_load_lds_dwordx4 v14, s[28:29]
	s_mov_b32 m0, s47
	s_nop 0
	global_load_lds_dwordx4 v136, s[100:101]
	s_mov_b32 m0, s48
	s_nop 0
	global_load_lds_dwordx4 v134, s[100:101]
	s_waitcnt vmcnt(8)
	s_waitcnt lgkmcnt(0)
	s_barrier
	s_setprio 1
	s_waitcnt lgkmcnt(0)
	v_mfma_f32_16x16x32_bf16 v[66:69], v[142:145], v[182:185], v[66:69]
	v_mfma_f32_16x16x32_bf16 v[66:69], v[146:149], v[186:189], v[66:69]
	v_mfma_f32_16x16x32_bf16 v[62:65], v[162:165], v[186:189], v[62:65]
	v_mfma_f32_16x16x32_bf16 v[62:65], v[150:153], v[182:185], v[62:65]
	v_mfma_f32_16x16x32_bf16 v[46:49], v[150:153], v[190:193], v[46:49]
	v_mfma_f32_16x16x32_bf16 v[46:49], v[162:165], v[194:197], v[46:49]
	v_mfma_f32_16x16x32_bf16 v[50:53], v[146:149], v[194:197], v[50:53]
	v_mfma_f32_16x16x32_bf16 v[50:53], v[142:145], v[190:193], v[50:53]
	v_mfma_f32_16x16x32_bf16 v[34:37], v[142:145], v[198:201], v[34:37]
	v_mfma_f32_16x16x32_bf16 v[34:37], v[146:149], v[206:209], v[34:37]
	v_mfma_f32_16x16x32_bf16 v[30:33], v[162:165], v[206:209], v[30:33]
	v_mfma_f32_16x16x32_bf16 v[30:33], v[150:153], v[198:201], v[30:33]
	v_mfma_f32_16x16x32_bf16 v[10:13], v[150:153], v[210:213], v[10:13]
	v_mfma_f32_16x16x32_bf16 v[10:13], v[162:165], v[214:217], v[10:13]
	v_mfma_f32_16x16x32_bf16 v[18:21], v[146:149], v[214:217], v[18:21]
	v_mfma_f32_16x16x32_bf16 v[18:21], v[142:145], v[210:213], v[18:21]
	s_setprio 0
	s_setprio 1
	v_mfma_f32_16x16x32_bf16 v[58:61], v[166:169], v[182:185], v[58:61]
	v_mfma_f32_16x16x32_bf16 v[58:61], v[170:173], v[186:189], v[58:61]
	v_mfma_f32_16x16x32_bf16 v[54:57], v[178:181], v[186:189], v[54:57]
	v_mfma_f32_16x16x32_bf16 v[54:57], v[174:177], v[182:185], v[54:57]
	v_mfma_f32_16x16x32_bf16 v[38:41], v[174:177], v[190:193], v[38:41]
	v_mfma_f32_16x16x32_bf16 v[38:41], v[178:181], v[194:197], v[38:41]
	v_mfma_f32_16x16x32_bf16 v[42:45], v[170:173], v[194:197], v[42:45]
	v_mfma_f32_16x16x32_bf16 v[42:45], v[166:169], v[190:193], v[42:45]
	v_mfma_f32_16x16x32_bf16 v[26:29], v[166:169], v[198:201], v[26:29]
	v_mfma_f32_16x16x32_bf16 v[26:29], v[170:173], v[206:209], v[26:29]
	v_mfma_f32_16x16x32_bf16 v[22:25], v[178:181], v[206:209], v[22:25]
	v_mfma_f32_16x16x32_bf16 v[22:25], v[174:177], v[198:201], v[22:25]
	v_mfma_f32_16x16x32_bf16 v[2:5], v[174:177], v[210:213], v[2:5]
	v_mfma_f32_16x16x32_bf16 v[2:5], v[178:181], v[214:217], v[2:5]
	v_mfma_f32_16x16x32_bf16 v[6:9], v[170:173], v[214:217], v[6:9]
	v_mfma_f32_16x16x32_bf16 v[6:9], v[166:169], v[210:213], v[6:9]
	s_setprio 0
	s_barrier
	s_add_i32 s56, s56, 2
	s_add_u32 s54, s54, 0x100
	s_addc_u32 s55, s55, 0
	s_add_u32 s26, s26, 0x100
	s_addc_u32 s27, s27, 0
	s_cmp_gt_u32 s56, 29
	s_cbranch_scc0 .LBB0_1223
	s_and_b64 vcc, exec, s[14:15]
	s_cbranch_vccz .LBB0_1226
	s_barrier
